# P12-row-pass-handwritten-16B-lanes-rows-in-flight
# baseline (speedup 1.0000x reference)
.LBB0_1346:
	s_cmp_lt_i32 s72, 13
	s_cselect_b64 s[4:5], -1, 0
	s_and_b64 s[0:1], s[4:5], s[0:1]
	s_andn2_b64 vcc, exec, s[0:1]
	s_cbranch_vccnz .LBB0_1353
	v_readlane_b32 s4, v242, 55
	s_cmpk_gt_i32 s4, 0x21ff
	v_readlane_b32 s5, v242, 56
	s_cbranch_scc1 .LBB0_1353
	s_waitcnt vmcnt(0)
	v_readlane_b32 s10, v242, 55
	v_lshlrev_b32_e32 v134, 5, v142
	v_lshlrev_b32_e32 v135, 4, v142
	v_mov_b32_e32 v133, 0x358637bd
	v_xor_b32_e32 v128, 1, v142
	v_lshlrev_b32_e32 v252, 2, v128
	v_xor_b32_e32 v128, 2, v142
	v_lshlrev_b32_e32 v253, 2, v128
	v_xor_b32_e32 v128, 4, v142
	v_lshlrev_b32_e32 v254, 2, v128
	v_xor_b32_e32 v128, 8, v142
	v_lshlrev_b32_e32 v255, 2, v128
	v_xor_b32_e32 v128, 16, v142
	v_lshlrev_b32_e32 v140, 2, v128
	v_xor_b32_e32 v128, 32, v142
	v_lshlrev_b32_e32 v141, 2, v128
	v_readlane_b32 s4, v242, 43
	v_readlane_b32 s5, v242, 44
	s_add_u32 s4, s4, 0x2000
	s_addc_u32 s5, s5, 0
	global_load_dwordx4 v[0:3], v134, s[4:5] offset:0
	global_load_dwordx4 v[4:7], v134, s[4:5] offset:16
	global_load_dwordx4 v[8:11], v134, s[4:5] offset:2048
	global_load_dwordx4 v[12:15], v134, s[4:5] offset:2064
	s_add_u32 s4, s4, 0x1000
	s_addc_u32 s5, s5, 0
	global_load_dwordx4 v[16:19], v134, s[4:5] offset:0
	global_load_dwordx4 v[20:23], v134, s[4:5] offset:16
	global_load_dwordx4 v[24:27], v134, s[4:5] offset:2048
	global_load_dwordx4 v[28:31], v134, s[4:5] offset:2064
	v_readlane_b32 s4, v242, 45
	v_readlane_b32 s5, v242, 46
	s_add_u32 s4, s4, 0x2000
	s_addc_u32 s5, s5, 0
	global_load_dwordx4 v[32:35], v134, s[4:5] offset:0
	global_load_dwordx4 v[36:39], v134, s[4:5] offset:16
	global_load_dwordx4 v[40:43], v134, s[4:5] offset:2048
	global_load_dwordx4 v[44:47], v134, s[4:5] offset:2064
	s_add_u32 s4, s4, 0x1000
	s_addc_u32 s5, s5, 0
	global_load_dwordx4 v[48:51], v134, s[4:5] offset:0
	global_load_dwordx4 v[52:55], v134, s[4:5] offset:16
	global_load_dwordx4 v[56:59], v134, s[4:5] offset:2048
	global_load_dwordx4 v[60:63], v134, s[4:5] offset:2064
	s_ashr_i32 s11, s10, 31
	s_lshl_b64 s[16:17], s[10:11], 12
	v_readlane_b32 s6, v242, 51
	v_readlane_b32 s7, v242, 52
	s_add_u32 s6, s6, s16
	s_addc_u32 s7, s7, s17
	s_mov_b64 s[12:13], s[6:7]
	s_add_u32 s8, s40, s16
	s_addc_u32 s9, s41, s17
	s_add_u32 s14, s70, s16
	s_addc_u32 s15, s71, s17
	s_add_u32 s14, s14, 0xc000000
	s_addc_u32 s15, s15, 0
	s_mov_b32 s3, 0x800000
	global_load_dwordx4 v[64:67], v135, s[6:7] offset:0
	global_load_dwordx4 v[68:71], v135, s[6:7] offset:1024
	global_load_dwordx4 v[72:75], v135, s[6:7] offset:2048
	global_load_dwordx4 v[76:79], v135, s[6:7] offset:3072
	global_load_dwordx4 v[80:83], v135, s[8:9] offset:0
	global_load_dwordx4 v[84:87], v135, s[8:9] offset:1024
	global_load_dwordx4 v[88:91], v135, s[8:9] offset:2048
	global_load_dwordx4 v[92:95], v135, s[8:9] offset:3072
	s_add_u32 s6, s6, 0x800000
	s_addc_u32 s7, s7, 0
	s_add_u32 s8, s8, 0x800000
	s_addc_u32 s9, s9, 0
	global_load_dwordx4 v[96:99], v135, s[6:7] offset:0
	global_load_dwordx4 v[100:103], v135, s[6:7] offset:1024
	global_load_dwordx4 v[104:107], v135, s[6:7] offset:2048
	global_load_dwordx4 v[108:111], v135, s[6:7] offset:3072
	global_load_dwordx4 v[112:115], v135, s[8:9] offset:0
	global_load_dwordx4 v[116:119], v135, s[8:9] offset:1024
	global_load_dwordx4 v[120:123], v135, s[8:9] offset:2048
	global_load_dwordx4 v[124:127], v135, s[8:9] offset:3072
	s_add_u32 s6, s6, 0x800000
	s_addc_u32 s7, s7, 0
	s_add_u32 s8, s8, 0x800000
	s_addc_u32 s9, s9, 0
	global_load_dwordx4 v[144:147], v135, s[6:7] offset:0
	global_load_dwordx4 v[148:151], v135, s[6:7] offset:1024
	global_load_dwordx4 v[152:155], v135, s[6:7] offset:2048
	global_load_dwordx4 v[156:159], v135, s[6:7] offset:3072
	global_load_dwordx4 v[160:163], v135, s[8:9] offset:0
	global_load_dwordx4 v[164:167], v135, s[8:9] offset:1024
	global_load_dwordx4 v[168:171], v135, s[8:9] offset:2048
	global_load_dwordx4 v[172:175], v135, s[8:9] offset:3072
	s_add_u32 s6, s6, 0x800000
	s_addc_u32 s7, s7, 0
	s_add_u32 s8, s8, 0x800000
	s_addc_u32 s9, s9, 0
	s_waitcnt vmcnt(16)
	global_load_dwordx4 v[176:179], v135, s[6:7] offset:0
	global_load_dwordx4 v[180:183], v135, s[6:7] offset:1024
	global_load_dwordx4 v[184:187], v135, s[6:7] offset:2048
	global_load_dwordx4 v[188:191], v135, s[6:7] offset:3072
	global_load_dwordx4 v[192:195], v135, s[8:9] offset:0
	global_load_dwordx4 v[196:199], v135, s[8:9] offset:1024
	global_load_dwordx4 v[200:203], v135, s[8:9] offset:2048
	global_load_dwordx4 v[204:207], v135, s[8:9] offset:3072
	s_add_u32 s6, s6, 0x800000
	s_addc_u32 s7, s7, 0
	s_add_u32 s8, s8, 0x800000
	s_addc_u32 s9, s9, 0
	v_lshlrev_b32_e32 v208, 16, v80
	v_and_b32_e32 v209, 0xffff0000, v80
	v_lshlrev_b32_e32 v210, 16, v81
	v_and_b32_e32 v211, 0xffff0000, v81
	v_lshlrev_b32_e32 v212, 16, v82
	v_and_b32_e32 v213, 0xffff0000, v82
	v_lshlrev_b32_e32 v214, 16, v83
	v_and_b32_e32 v215, 0xffff0000, v83
	v_lshlrev_b32_e32 v216, 16, v84
	v_and_b32_e32 v217, 0xffff0000, v84
	v_lshlrev_b32_e32 v218, 16, v85
	v_and_b32_e32 v219, 0xffff0000, v85
	v_lshlrev_b32_e32 v220, 16, v86
	v_and_b32_e32 v221, 0xffff0000, v86
	v_lshlrev_b32_e32 v222, 16, v87
	v_and_b32_e32 v223, 0xffff0000, v87
	v_lshlrev_b32_e32 v224, 16, v88
	v_and_b32_e32 v225, 0xffff0000, v88
	v_lshlrev_b32_e32 v226, 16, v89
	v_and_b32_e32 v227, 0xffff0000, v89
	v_lshlrev_b32_e32 v228, 16, v90
	v_and_b32_e32 v229, 0xffff0000, v90
	v_lshlrev_b32_e32 v230, 16, v91
	v_and_b32_e32 v231, 0xffff0000, v91
	v_lshlrev_b32_e32 v232, 16, v92
	v_and_b32_e32 v233, 0xffff0000, v92
	v_lshlrev_b32_e32 v234, 16, v93
	v_and_b32_e32 v235, 0xffff0000, v93
	v_lshlrev_b32_e32 v236, 16, v94
	v_and_b32_e32 v237, 0xffff0000, v94
	v_lshlrev_b32_e32 v238, 16, v95
	v_and_b32_e32 v239, 0xffff0000, v95
	v_mul_f32_e32 v128, v208, v208
	v_fmac_f32_e32 v128, v209, v209
	v_mul_f32_e32 v129, v210, v210
	v_fmac_f32_e32 v129, v211, v211
	v_add_f32_e32 v128, v128, v129
	v_mul_f32_e32 v129, v212, v212
	v_fmac_f32_e32 v129, v213, v213
	v_mul_f32_e32 v132, v214, v214
	v_fmac_f32_e32 v132, v215, v215
	v_add_f32_e32 v129, v129, v132
	v_add_f32_e32 v128, v128, v129
	v_mul_f32_e32 v129, v216, v216
	v_fmac_f32_e32 v129, v217, v217
	v_mul_f32_e32 v132, v218, v218
	v_fmac_f32_e32 v132, v219, v219
	v_add_f32_e32 v129, v129, v132
	v_add_f32_e32 v128, v128, v129
	v_mul_f32_e32 v129, v220, v220
	v_fmac_f32_e32 v129, v221, v221
	v_mul_f32_e32 v132, v222, v222
	v_fmac_f32_e32 v132, v223, v223
	v_add_f32_e32 v129, v129, v132
	v_add_f32_e32 v128, v128, v129
	v_mul_f32_e32 v129, v224, v224
	v_fmac_f32_e32 v129, v225, v225
	v_mul_f32_e32 v132, v226, v226
	v_fmac_f32_e32 v132, v227, v227
	v_add_f32_e32 v129, v129, v132
	v_add_f32_e32 v128, v128, v129
	v_mul_f32_e32 v129, v228, v228
	v_fmac_f32_e32 v129, v229, v229
	v_mul_f32_e32 v132, v230, v230
	v_fmac_f32_e32 v132, v231, v231
	v_add_f32_e32 v129, v129, v132
	v_add_f32_e32 v128, v128, v129
	v_mul_f32_e32 v129, v232, v232
	v_fmac_f32_e32 v129, v233, v233
	v_mul_f32_e32 v132, v234, v234
	v_fmac_f32_e32 v132, v235, v235
	v_add_f32_e32 v129, v129, v132
	v_add_f32_e32 v128, v128, v129
	v_mul_f32_e32 v129, v236, v236
	v_fmac_f32_e32 v129, v237, v237
	v_mul_f32_e32 v132, v238, v238
	v_fmac_f32_e32 v132, v239, v239
	v_add_f32_e32 v129, v129, v132
	v_add_f32_e32 v128, v128, v129
	ds_bpermute_b32 v129, v252, v128
	s_waitcnt lgkmcnt(0)
	v_add_f32_e32 v128, v128, v129
	ds_bpermute_b32 v129, v253, v128
	s_waitcnt lgkmcnt(0)
	v_add_f32_e32 v128, v128, v129
	ds_bpermute_b32 v129, v254, v128
	s_waitcnt lgkmcnt(0)
	v_add_f32_e32 v128, v128, v129
	ds_bpermute_b32 v129, v255, v128
	s_waitcnt lgkmcnt(0)
	v_add_f32_e32 v128, v128, v129
	ds_bpermute_b32 v129, v140, v128
	s_waitcnt lgkmcnt(0)
	v_add_f32_e32 v128, v128, v129
	ds_bpermute_b32 v129, v141, v128
	s_waitcnt lgkmcnt(0)
	v_add_f32_e32 v128, v128, v129
	v_fmamk_f32 v128, v128, 0x3a000000, v133
	v_mul_f32_e32 v129, 0x4b800000, v128
	v_cmp_gt_f32_e32 vcc, s3, v128
	s_nop 1
	v_cndmask_b32_e32 v128, v128, v129, vcc
	v_rsq_f32_e32 v128, v128
	s_nop 0
	v_mul_f32_e32 v129, 0x45800000, v128
	v_cndmask_b32_e32 v130, v128, v129, vcc
	v_lshlrev_b32_e32 v244, 16, v64
	v_and_b32_e32 v245, 0xffff0000, v64
	v_lshlrev_b32_e32 v246, 16, v65
	v_and_b32_e32 v247, 0xffff0000, v65
	v_lshlrev_b32_e32 v248, 16, v66
	v_and_b32_e32 v249, 0xffff0000, v66
	v_lshlrev_b32_e32 v250, 16, v67
	v_and_b32_e32 v251, 0xffff0000, v67
	v_pk_mul_f32 v[208:209], v[130:131], v[208:209] op_sel_hi:[0,1]
	v_pk_fma_f32 v[208:209], v[0:1], v[208:209], v[244:245]
	v_pk_mul_f32 v[210:211], v[130:131], v[210:211] op_sel_hi:[0,1]
	v_pk_fma_f32 v[210:211], v[2:3], v[210:211], v[246:247]
	v_pk_mul_f32 v[212:213], v[130:131], v[212:213] op_sel_hi:[0,1]
	v_pk_fma_f32 v[212:213], v[4:5], v[212:213], v[248:249]
	v_pk_mul_f32 v[214:215], v[130:131], v[214:215] op_sel_hi:[0,1]
	v_pk_fma_f32 v[214:215], v[6:7], v[214:215], v[250:251]
	v_cvt_pk_bf16_f32 v136, v208, v209
	v_cvt_pk_bf16_f32 v137, v210, v211
	v_cvt_pk_bf16_f32 v138, v212, v213
	v_cvt_pk_bf16_f32 v139, v214, v215
	global_store_dwordx4 v135, v[136:139], s[12:13] offset:0
	s_nop 1
	v_lshlrev_b32_e32 v244, 16, v68
	v_and_b32_e32 v245, 0xffff0000, v68
	v_lshlrev_b32_e32 v246, 16, v69
	v_and_b32_e32 v247, 0xffff0000, v69
	v_lshlrev_b32_e32 v248, 16, v70
	v_and_b32_e32 v249, 0xffff0000, v70
	v_lshlrev_b32_e32 v250, 16, v71
	v_and_b32_e32 v251, 0xffff0000, v71
	v_pk_mul_f32 v[216:217], v[130:131], v[216:217] op_sel_hi:[0,1]
	v_pk_fma_f32 v[216:217], v[8:9], v[216:217], v[244:245]
	v_pk_mul_f32 v[218:219], v[130:131], v[218:219] op_sel_hi:[0,1]
	v_pk_fma_f32 v[218:219], v[10:11], v[218:219], v[246:247]
	v_pk_mul_f32 v[220:221], v[130:131], v[220:221] op_sel_hi:[0,1]
	v_pk_fma_f32 v[220:221], v[12:13], v[220:221], v[248:249]
	v_pk_mul_f32 v[222:223], v[130:131], v[222:223] op_sel_hi:[0,1]
	v_pk_fma_f32 v[222:223], v[14:15], v[222:223], v[250:251]
	v_cvt_pk_bf16_f32 v136, v216, v217
	v_cvt_pk_bf16_f32 v137, v218, v219
	v_cvt_pk_bf16_f32 v138, v220, v221
	v_cvt_pk_bf16_f32 v139, v222, v223
	global_store_dwordx4 v135, v[136:139], s[12:13] offset:1024
	s_nop 1
	v_lshlrev_b32_e32 v244, 16, v72
	v_and_b32_e32 v245, 0xffff0000, v72
	v_lshlrev_b32_e32 v246, 16, v73
	v_and_b32_e32 v247, 0xffff0000, v73
	v_lshlrev_b32_e32 v248, 16, v74
	v_and_b32_e32 v249, 0xffff0000, v74
	v_lshlrev_b32_e32 v250, 16, v75
	v_and_b32_e32 v251, 0xffff0000, v75
	v_pk_mul_f32 v[224:225], v[130:131], v[224:225] op_sel_hi:[0,1]
	v_pk_fma_f32 v[224:225], v[16:17], v[224:225], v[244:245]
	v_pk_mul_f32 v[226:227], v[130:131], v[226:227] op_sel_hi:[0,1]
	v_pk_fma_f32 v[226:227], v[18:19], v[226:227], v[246:247]
	v_pk_mul_f32 v[228:229], v[130:131], v[228:229] op_sel_hi:[0,1]
	v_pk_fma_f32 v[228:229], v[20:21], v[228:229], v[248:249]
	v_pk_mul_f32 v[230:231], v[130:131], v[230:231] op_sel_hi:[0,1]
	v_pk_fma_f32 v[230:231], v[22:23], v[230:231], v[250:251]
	v_cvt_pk_bf16_f32 v136, v224, v225
	v_cvt_pk_bf16_f32 v137, v226, v227
	v_cvt_pk_bf16_f32 v138, v228, v229
	v_cvt_pk_bf16_f32 v139, v230, v231
	global_store_dwordx4 v135, v[136:139], s[12:13] offset:2048
	s_nop 1
	v_lshlrev_b32_e32 v244, 16, v76
	v_and_b32_e32 v245, 0xffff0000, v76
	v_lshlrev_b32_e32 v246, 16, v77
	v_and_b32_e32 v247, 0xffff0000, v77
	v_lshlrev_b32_e32 v248, 16, v78
	v_and_b32_e32 v249, 0xffff0000, v78
	v_lshlrev_b32_e32 v250, 16, v79
	v_and_b32_e32 v251, 0xffff0000, v79
	v_pk_mul_f32 v[232:233], v[130:131], v[232:233] op_sel_hi:[0,1]
	v_pk_fma_f32 v[232:233], v[24:25], v[232:233], v[244:245]
	v_pk_mul_f32 v[234:235], v[130:131], v[234:235] op_sel_hi:[0,1]
	v_pk_fma_f32 v[234:235], v[26:27], v[234:235], v[246:247]
	v_pk_mul_f32 v[236:237], v[130:131], v[236:237] op_sel_hi:[0,1]
	v_pk_fma_f32 v[236:237], v[28:29], v[236:237], v[248:249]
	v_pk_mul_f32 v[238:239], v[130:131], v[238:239] op_sel_hi:[0,1]
	v_pk_fma_f32 v[238:239], v[30:31], v[238:239], v[250:251]
	v_cvt_pk_bf16_f32 v136, v232, v233
	v_cvt_pk_bf16_f32 v137, v234, v235
	v_cvt_pk_bf16_f32 v138, v236, v237
	v_cvt_pk_bf16_f32 v139, v238, v239
	global_store_dwordx4 v135, v[136:139], s[12:13] offset:3072
	s_nop 1
	v_mul_f32_e32 v128, v208, v208
	v_fmac_f32_e32 v128, v209, v209
	v_mul_f32_e32 v129, v210, v210
	v_fmac_f32_e32 v129, v211, v211
	v_add_f32_e32 v128, v128, v129
	v_mul_f32_e32 v129, v212, v212
	v_fmac_f32_e32 v129, v213, v213
	v_mul_f32_e32 v132, v214, v214
	v_fmac_f32_e32 v132, v215, v215
	v_add_f32_e32 v129, v129, v132
	v_add_f32_e32 v128, v128, v129
	v_mul_f32_e32 v129, v216, v216
	v_fmac_f32_e32 v129, v217, v217
	v_mul_f32_e32 v132, v218, v218
	v_fmac_f32_e32 v132, v219, v219
	v_add_f32_e32 v129, v129, v132
	v_add_f32_e32 v128, v128, v129
	v_mul_f32_e32 v129, v220, v220
	v_fmac_f32_e32 v129, v221, v221
	v_mul_f32_e32 v132, v222, v222
	v_fmac_f32_e32 v132, v223, v223
	v_add_f32_e32 v129, v129, v132
	v_add_f32_e32 v128, v128, v129
	v_mul_f32_e32 v129, v224, v224
	v_fmac_f32_e32 v129, v225, v225
	v_mul_f32_e32 v132, v226, v226
	v_fmac_f32_e32 v132, v227, v227
	v_add_f32_e32 v129, v129, v132
	v_add_f32_e32 v128, v128, v129
	v_mul_f32_e32 v129, v228, v228
	v_fmac_f32_e32 v129, v229, v229
	v_mul_f32_e32 v132, v230, v230
	v_fmac_f32_e32 v132, v231, v231
	v_add_f32_e32 v129, v129, v132
	v_add_f32_e32 v128, v128, v129
	v_mul_f32_e32 v129, v232, v232
	v_fmac_f32_e32 v129, v233, v233
	v_mul_f32_e32 v132, v234, v234
	v_fmac_f32_e32 v132, v235, v235
	v_add_f32_e32 v129, v129, v132
	v_add_f32_e32 v128, v128, v129
	v_mul_f32_e32 v129, v236, v236
	v_fmac_f32_e32 v129, v237, v237
	v_mul_f32_e32 v132, v238, v238
	v_fmac_f32_e32 v132, v239, v239
	v_add_f32_e32 v129, v129, v132
	v_add_f32_e32 v128, v128, v129
	ds_bpermute_b32 v129, v252, v128
	s_waitcnt lgkmcnt(0)
	v_add_f32_e32 v128, v128, v129
	ds_bpermute_b32 v129, v253, v128
	s_waitcnt lgkmcnt(0)
	v_add_f32_e32 v128, v128, v129
	ds_bpermute_b32 v129, v254, v128
	s_waitcnt lgkmcnt(0)
	v_add_f32_e32 v128, v128, v129
	ds_bpermute_b32 v129, v255, v128
	s_waitcnt lgkmcnt(0)
	v_add_f32_e32 v128, v128, v129
	ds_bpermute_b32 v129, v140, v128
	s_waitcnt lgkmcnt(0)
	v_add_f32_e32 v128, v128, v129
	ds_bpermute_b32 v129, v141, v128
	s_waitcnt lgkmcnt(0)
	v_add_f32_e32 v128, v128, v129
	v_fmamk_f32 v128, v128, 0x3a000000, v133
	v_mul_f32_e32 v129, 0x4b800000, v128
	v_cmp_gt_f32_e32 vcc, s3, v128
	s_nop 1
	v_cndmask_b32_e32 v128, v128, v129, vcc
	v_rsq_f32_e32 v128, v128
	s_nop 0
	v_mul_f32_e32 v129, 0x45800000, v128
	v_cndmask_b32_e32 v130, v128, v129, vcc
	v_pk_mul_f32 v[208:209], v[208:209], v[130:131] op_sel_hi:[1,0]
	v_pk_mul_f32 v[208:209], v[32:33], v[208:209]
	v_pk_mul_f32 v[210:211], v[210:211], v[130:131] op_sel_hi:[1,0]
	v_pk_mul_f32 v[210:211], v[34:35], v[210:211]
	v_pk_mul_f32 v[212:213], v[212:213], v[130:131] op_sel_hi:[1,0]
	v_pk_mul_f32 v[212:213], v[36:37], v[212:213]
	v_pk_mul_f32 v[214:215], v[214:215], v[130:131] op_sel_hi:[1,0]
	v_pk_mul_f32 v[214:215], v[38:39], v[214:215]
	v_cvt_pk_bf16_f32 v136, v208, v209
	v_cvt_pk_bf16_f32 v137, v210, v211
	v_cvt_pk_bf16_f32 v138, v212, v213
	v_cvt_pk_bf16_f32 v139, v214, v215
	global_store_dwordx4 v135, v[136:139], s[14:15] offset:0
	s_nop 1
	v_pk_mul_f32 v[216:217], v[216:217], v[130:131] op_sel_hi:[1,0]
	v_pk_mul_f32 v[216:217], v[40:41], v[216:217]
	v_pk_mul_f32 v[218:219], v[218:219], v[130:131] op_sel_hi:[1,0]
	v_pk_mul_f32 v[218:219], v[42:43], v[218:219]
	v_pk_mul_f32 v[220:221], v[220:221], v[130:131] op_sel_hi:[1,0]
	v_pk_mul_f32 v[220:221], v[44:45], v[220:221]
	v_pk_mul_f32 v[222:223], v[222:223], v[130:131] op_sel_hi:[1,0]
	v_pk_mul_f32 v[222:223], v[46:47], v[222:223]
	v_cvt_pk_bf16_f32 v136, v216, v217
	v_cvt_pk_bf16_f32 v137, v218, v219
	v_cvt_pk_bf16_f32 v138, v220, v221
	v_cvt_pk_bf16_f32 v139, v222, v223
	global_store_dwordx4 v135, v[136:139], s[14:15] offset:1024
	s_nop 1
	v_pk_mul_f32 v[224:225], v[224:225], v[130:131] op_sel_hi:[1,0]
	v_pk_mul_f32 v[224:225], v[48:49], v[224:225]
	v_pk_mul_f32 v[226:227], v[226:227], v[130:131] op_sel_hi:[1,0]
	v_pk_mul_f32 v[226:227], v[50:51], v[226:227]
	v_pk_mul_f32 v[228:229], v[228:229], v[130:131] op_sel_hi:[1,0]
	v_pk_mul_f32 v[228:229], v[52:53], v[228:229]
	v_pk_mul_f32 v[230:231], v[230:231], v[130:131] op_sel_hi:[1,0]
	v_pk_mul_f32 v[230:231], v[54:55], v[230:231]
	v_cvt_pk_bf16_f32 v136, v224, v225
	v_cvt_pk_bf16_f32 v137, v226, v227
	v_cvt_pk_bf16_f32 v138, v228, v229
	v_cvt_pk_bf16_f32 v139, v230, v231
	global_store_dwordx4 v135, v[136:139], s[14:15] offset:2048
	s_nop 1
	v_pk_mul_f32 v[232:233], v[232:233], v[130:131] op_sel_hi:[1,0]
	v_pk_mul_f32 v[232:233], v[56:57], v[232:233]
	v_pk_mul_f32 v[234:235], v[234:235], v[130:131] op_sel_hi:[1,0]
	v_pk_mul_f32 v[234:235], v[58:59], v[234:235]
	v_pk_mul_f32 v[236:237], v[236:237], v[130:131] op_sel_hi:[1,0]
	v_pk_mul_f32 v[236:237], v[60:61], v[236:237]
	v_pk_mul_f32 v[238:239], v[238:239], v[130:131] op_sel_hi:[1,0]
	v_pk_mul_f32 v[238:239], v[62:63], v[238:239]
	v_cvt_pk_bf16_f32 v136, v232, v233
	v_cvt_pk_bf16_f32 v137, v234, v235
	v_cvt_pk_bf16_f32 v138, v236, v237
	v_cvt_pk_bf16_f32 v139, v238, v239
	global_store_dwordx4 v135, v[136:139], s[14:15] offset:3072
	s_nop 1
	s_add_u32 s12, s12, 0x800000
	s_addc_u32 s13, s13, 0
	s_add_u32 s14, s14, 0x800000
	s_addc_u32 s15, s15, 0
	s_waitcnt vmcnt(24)
	s_cmpk_gt_i32 s10, 0x1ff
	s_cbranch_scc1 .Lp12_no5a
	global_load_dwordx4 v[64:67], v135, s[6:7] offset:0
	global_load_dwordx4 v[68:71], v135, s[6:7] offset:1024
	global_load_dwordx4 v[72:75], v135, s[6:7] offset:2048
	global_load_dwordx4 v[76:79], v135, s[6:7] offset:3072
	global_load_dwordx4 v[80:83], v135, s[8:9] offset:0
	global_load_dwordx4 v[84:87], v135, s[8:9] offset:1024
	global_load_dwordx4 v[88:91], v135, s[8:9] offset:2048
	global_load_dwordx4 v[92:95], v135, s[8:9] offset:3072
	s_add_u32 s6, s6, 0x800000
	s_addc_u32 s7, s7, 0
	s_add_u32 s8, s8, 0x800000
	s_addc_u32 s9, s9, 0
.Lp12_no5a:
	v_lshlrev_b32_e32 v208, 16, v112
	v_and_b32_e32 v209, 0xffff0000, v112
	v_lshlrev_b32_e32 v210, 16, v113
	v_and_b32_e32 v211, 0xffff0000, v113
	v_lshlrev_b32_e32 v212, 16, v114
	v_and_b32_e32 v213, 0xffff0000, v114
	v_lshlrev_b32_e32 v214, 16, v115
	v_and_b32_e32 v215, 0xffff0000, v115
	v_lshlrev_b32_e32 v216, 16, v116
	v_and_b32_e32 v217, 0xffff0000, v116
	v_lshlrev_b32_e32 v218, 16, v117
	v_and_b32_e32 v219, 0xffff0000, v117
	v_lshlrev_b32_e32 v220, 16, v118
	v_and_b32_e32 v221, 0xffff0000, v118
	v_lshlrev_b32_e32 v222, 16, v119
	v_and_b32_e32 v223, 0xffff0000, v119
	v_lshlrev_b32_e32 v224, 16, v120
	v_and_b32_e32 v225, 0xffff0000, v120
	v_lshlrev_b32_e32 v226, 16, v121
	v_and_b32_e32 v227, 0xffff0000, v121
	v_lshlrev_b32_e32 v228, 16, v122
	v_and_b32_e32 v229, 0xffff0000, v122
	v_lshlrev_b32_e32 v230, 16, v123
	v_and_b32_e32 v231, 0xffff0000, v123
	v_lshlrev_b32_e32 v232, 16, v124
	v_and_b32_e32 v233, 0xffff0000, v124
	v_lshlrev_b32_e32 v234, 16, v125
	v_and_b32_e32 v235, 0xffff0000, v125
	v_lshlrev_b32_e32 v236, 16, v126
	v_and_b32_e32 v237, 0xffff0000, v126
	v_lshlrev_b32_e32 v238, 16, v127
	v_and_b32_e32 v239, 0xffff0000, v127
	v_mul_f32_e32 v128, v208, v208
	v_fmac_f32_e32 v128, v209, v209
	v_mul_f32_e32 v129, v210, v210
	v_fmac_f32_e32 v129, v211, v211
	v_add_f32_e32 v128, v128, v129
	v_mul_f32_e32 v129, v212, v212
	v_fmac_f32_e32 v129, v213, v213
	v_mul_f32_e32 v132, v214, v214
	v_fmac_f32_e32 v132, v215, v215
	v_add_f32_e32 v129, v129, v132
	v_add_f32_e32 v128, v128, v129
	v_mul_f32_e32 v129, v216, v216
	v_fmac_f32_e32 v129, v217, v217
	v_mul_f32_e32 v132, v218, v218
	v_fmac_f32_e32 v132, v219, v219
	v_add_f32_e32 v129, v129, v132
	v_add_f32_e32 v128, v128, v129
	v_mul_f32_e32 v129, v220, v220
	v_fmac_f32_e32 v129, v221, v221
	v_mul_f32_e32 v132, v222, v222
	v_fmac_f32_e32 v132, v223, v223
	v_add_f32_e32 v129, v129, v132
	v_add_f32_e32 v128, v128, v129
	v_mul_f32_e32 v129, v224, v224
	v_fmac_f32_e32 v129, v225, v225
	v_mul_f32_e32 v132, v226, v226
	v_fmac_f32_e32 v132, v227, v227
	v_add_f32_e32 v129, v129, v132
	v_add_f32_e32 v128, v128, v129
	v_mul_f32_e32 v129, v228, v228
	v_fmac_f32_e32 v129, v229, v229
	v_mul_f32_e32 v132, v230, v230
	v_fmac_f32_e32 v132, v231, v231
	v_add_f32_e32 v129, v129, v132
	v_add_f32_e32 v128, v128, v129
	v_mul_f32_e32 v129, v232, v232
	v_fmac_f32_e32 v129, v233, v233
	v_mul_f32_e32 v132, v234, v234
	v_fmac_f32_e32 v132, v235, v235
	v_add_f32_e32 v129, v129, v132
	v_add_f32_e32 v128, v128, v129
	v_mul_f32_e32 v129, v236, v236
	v_fmac_f32_e32 v129, v237, v237
	v_mul_f32_e32 v132, v238, v238
	v_fmac_f32_e32 v132, v239, v239
	v_add_f32_e32 v129, v129, v132
	v_add_f32_e32 v128, v128, v129
	ds_bpermute_b32 v129, v252, v128
	s_waitcnt lgkmcnt(0)
	v_add_f32_e32 v128, v128, v129
	ds_bpermute_b32 v129, v253, v128
	s_waitcnt lgkmcnt(0)
	v_add_f32_e32 v128, v128, v129
	ds_bpermute_b32 v129, v254, v128
	s_waitcnt lgkmcnt(0)
	v_add_f32_e32 v128, v128, v129
	ds_bpermute_b32 v129, v255, v128
	s_waitcnt lgkmcnt(0)
	v_add_f32_e32 v128, v128, v129
	ds_bpermute_b32 v129, v140, v128
	s_waitcnt lgkmcnt(0)
	v_add_f32_e32 v128, v128, v129
	ds_bpermute_b32 v129, v141, v128
	s_waitcnt lgkmcnt(0)
	v_add_f32_e32 v128, v128, v129
	v_fmamk_f32 v128, v128, 0x3a000000, v133
	v_mul_f32_e32 v129, 0x4b800000, v128
	v_cmp_gt_f32_e32 vcc, s3, v128
	s_nop 1
	v_cndmask_b32_e32 v128, v128, v129, vcc
	v_rsq_f32_e32 v128, v128
	s_nop 0
	v_mul_f32_e32 v129, 0x45800000, v128
	v_cndmask_b32_e32 v130, v128, v129, vcc
	v_lshlrev_b32_e32 v244, 16, v96
	v_and_b32_e32 v245, 0xffff0000, v96
	v_lshlrev_b32_e32 v246, 16, v97
	v_and_b32_e32 v247, 0xffff0000, v97
	v_lshlrev_b32_e32 v248, 16, v98
	v_and_b32_e32 v249, 0xffff0000, v98
	v_lshlrev_b32_e32 v250, 16, v99
	v_and_b32_e32 v251, 0xffff0000, v99
	v_pk_mul_f32 v[208:209], v[130:131], v[208:209] op_sel_hi:[0,1]
	v_pk_fma_f32 v[208:209], v[0:1], v[208:209], v[244:245]
	v_pk_mul_f32 v[210:211], v[130:131], v[210:211] op_sel_hi:[0,1]
	v_pk_fma_f32 v[210:211], v[2:3], v[210:211], v[246:247]
	v_pk_mul_f32 v[212:213], v[130:131], v[212:213] op_sel_hi:[0,1]
	v_pk_fma_f32 v[212:213], v[4:5], v[212:213], v[248:249]
	v_pk_mul_f32 v[214:215], v[130:131], v[214:215] op_sel_hi:[0,1]
	v_pk_fma_f32 v[214:215], v[6:7], v[214:215], v[250:251]
	v_cvt_pk_bf16_f32 v136, v208, v209
	v_cvt_pk_bf16_f32 v137, v210, v211
	v_cvt_pk_bf16_f32 v138, v212, v213
	v_cvt_pk_bf16_f32 v139, v214, v215
	global_store_dwordx4 v135, v[136:139], s[12:13] offset:0
	s_nop 1
	v_lshlrev_b32_e32 v244, 16, v100
	v_and_b32_e32 v245, 0xffff0000, v100
	v_lshlrev_b32_e32 v246, 16, v101
	v_and_b32_e32 v247, 0xffff0000, v101
	v_lshlrev_b32_e32 v248, 16, v102
	v_and_b32_e32 v249, 0xffff0000, v102
	v_lshlrev_b32_e32 v250, 16, v103
	v_and_b32_e32 v251, 0xffff0000, v103
	v_pk_mul_f32 v[216:217], v[130:131], v[216:217] op_sel_hi:[0,1]
	v_pk_fma_f32 v[216:217], v[8:9], v[216:217], v[244:245]
	v_pk_mul_f32 v[218:219], v[130:131], v[218:219] op_sel_hi:[0,1]
	v_pk_fma_f32 v[218:219], v[10:11], v[218:219], v[246:247]
	v_pk_mul_f32 v[220:221], v[130:131], v[220:221] op_sel_hi:[0,1]
	v_pk_fma_f32 v[220:221], v[12:13], v[220:221], v[248:249]
	v_pk_mul_f32 v[222:223], v[130:131], v[222:223] op_sel_hi:[0,1]
	v_pk_fma_f32 v[222:223], v[14:15], v[222:223], v[250:251]
	v_cvt_pk_bf16_f32 v136, v216, v217
	v_cvt_pk_bf16_f32 v137, v218, v219
	v_cvt_pk_bf16_f32 v138, v220, v221
	v_cvt_pk_bf16_f32 v139, v222, v223
	global_store_dwordx4 v135, v[136:139], s[12:13] offset:1024
	s_nop 1
	v_lshlrev_b32_e32 v244, 16, v104
	v_and_b32_e32 v245, 0xffff0000, v104
	v_lshlrev_b32_e32 v246, 16, v105
	v_and_b32_e32 v247, 0xffff0000, v105
	v_lshlrev_b32_e32 v248, 16, v106
	v_and_b32_e32 v249, 0xffff0000, v106
	v_lshlrev_b32_e32 v250, 16, v107
	v_and_b32_e32 v251, 0xffff0000, v107
	v_pk_mul_f32 v[224:225], v[130:131], v[224:225] op_sel_hi:[0,1]
	v_pk_fma_f32 v[224:225], v[16:17], v[224:225], v[244:245]
	v_pk_mul_f32 v[226:227], v[130:131], v[226:227] op_sel_hi:[0,1]
	v_pk_fma_f32 v[226:227], v[18:19], v[226:227], v[246:247]
	v_pk_mul_f32 v[228:229], v[130:131], v[228:229] op_sel_hi:[0,1]
	v_pk_fma_f32 v[228:229], v[20:21], v[228:229], v[248:249]
	v_pk_mul_f32 v[230:231], v[130:131], v[230:231] op_sel_hi:[0,1]
	v_pk_fma_f32 v[230:231], v[22:23], v[230:231], v[250:251]
	v_cvt_pk_bf16_f32 v136, v224, v225
	v_cvt_pk_bf16_f32 v137, v226, v227
	v_cvt_pk_bf16_f32 v138, v228, v229
	v_cvt_pk_bf16_f32 v139, v230, v231
	global_store_dwordx4 v135, v[136:139], s[12:13] offset:2048
	s_nop 1
	v_lshlrev_b32_e32 v244, 16, v108
	v_and_b32_e32 v245, 0xffff0000, v108
	v_lshlrev_b32_e32 v246, 16, v109
	v_and_b32_e32 v247, 0xffff0000, v109
	v_lshlrev_b32_e32 v248, 16, v110
	v_and_b32_e32 v249, 0xffff0000, v110
	v_lshlrev_b32_e32 v250, 16, v111
	v_and_b32_e32 v251, 0xffff0000, v111
	v_pk_mul_f32 v[232:233], v[130:131], v[232:233] op_sel_hi:[0,1]
	v_pk_fma_f32 v[232:233], v[24:25], v[232:233], v[244:245]
	v_pk_mul_f32 v[234:235], v[130:131], v[234:235] op_sel_hi:[0,1]
	v_pk_fma_f32 v[234:235], v[26:27], v[234:235], v[246:247]
	v_pk_mul_f32 v[236:237], v[130:131], v[236:237] op_sel_hi:[0,1]
	v_pk_fma_f32 v[236:237], v[28:29], v[236:237], v[248:249]
	v_pk_mul_f32 v[238:239], v[130:131], v[238:239] op_sel_hi:[0,1]
	v_pk_fma_f32 v[238:239], v[30:31], v[238:239], v[250:251]
	v_cvt_pk_bf16_f32 v136, v232, v233
	v_cvt_pk_bf16_f32 v137, v234, v235
	v_cvt_pk_bf16_f32 v138, v236, v237
	v_cvt_pk_bf16_f32 v139, v238, v239
	global_store_dwordx4 v135, v[136:139], s[12:13] offset:3072
	s_nop 1
	v_mul_f32_e32 v128, v208, v208
	v_fmac_f32_e32 v128, v209, v209
	v_mul_f32_e32 v129, v210, v210
	v_fmac_f32_e32 v129, v211, v211
	v_add_f32_e32 v128, v128, v129
	v_mul_f32_e32 v129, v212, v212
	v_fmac_f32_e32 v129, v213, v213
	v_mul_f32_e32 v132, v214, v214
	v_fmac_f32_e32 v132, v215, v215
	v_add_f32_e32 v129, v129, v132
	v_add_f32_e32 v128, v128, v129
	v_mul_f32_e32 v129, v216, v216
	v_fmac_f32_e32 v129, v217, v217
	v_mul_f32_e32 v132, v218, v218
	v_fmac_f32_e32 v132, v219, v219
	v_add_f32_e32 v129, v129, v132
	v_add_f32_e32 v128, v128, v129
	v_mul_f32_e32 v129, v220, v220
	v_fmac_f32_e32 v129, v221, v221
	v_mul_f32_e32 v132, v222, v222
	v_fmac_f32_e32 v132, v223, v223
	v_add_f32_e32 v129, v129, v132
	v_add_f32_e32 v128, v128, v129
	v_mul_f32_e32 v129, v224, v224
	v_fmac_f32_e32 v129, v225, v225
	v_mul_f32_e32 v132, v226, v226
	v_fmac_f32_e32 v132, v227, v227
	v_add_f32_e32 v129, v129, v132
	v_add_f32_e32 v128, v128, v129
	v_mul_f32_e32 v129, v228, v228
	v_fmac_f32_e32 v129, v229, v229
	v_mul_f32_e32 v132, v230, v230
	v_fmac_f32_e32 v132, v231, v231
	v_add_f32_e32 v129, v129, v132
	v_add_f32_e32 v128, v128, v129
	v_mul_f32_e32 v129, v232, v232
	v_fmac_f32_e32 v129, v233, v233
	v_mul_f32_e32 v132, v234, v234
	v_fmac_f32_e32 v132, v235, v235
	v_add_f32_e32 v129, v129, v132
	v_add_f32_e32 v128, v128, v129
	v_mul_f32_e32 v129, v236, v236
	v_fmac_f32_e32 v129, v237, v237
	v_mul_f32_e32 v132, v238, v238
	v_fmac_f32_e32 v132, v239, v239
	v_add_f32_e32 v129, v129, v132
	v_add_f32_e32 v128, v128, v129
	ds_bpermute_b32 v129, v252, v128
	s_waitcnt lgkmcnt(0)
	v_add_f32_e32 v128, v128, v129
	ds_bpermute_b32 v129, v253, v128
	s_waitcnt lgkmcnt(0)
	v_add_f32_e32 v128, v128, v129
	ds_bpermute_b32 v129, v254, v128
	s_waitcnt lgkmcnt(0)
	v_add_f32_e32 v128, v128, v129
	ds_bpermute_b32 v129, v255, v128
	s_waitcnt lgkmcnt(0)
	v_add_f32_e32 v128, v128, v129
	ds_bpermute_b32 v129, v140, v128
	s_waitcnt lgkmcnt(0)
	v_add_f32_e32 v128, v128, v129
	ds_bpermute_b32 v129, v141, v128
	s_waitcnt lgkmcnt(0)
	v_add_f32_e32 v128, v128, v129
	v_fmamk_f32 v128, v128, 0x3a000000, v133
	v_mul_f32_e32 v129, 0x4b800000, v128
	v_cmp_gt_f32_e32 vcc, s3, v128
	s_nop 1
	v_cndmask_b32_e32 v128, v128, v129, vcc
	v_rsq_f32_e32 v128, v128
	s_nop 0
	v_mul_f32_e32 v129, 0x45800000, v128
	v_cndmask_b32_e32 v130, v128, v129, vcc
	v_pk_mul_f32 v[208:209], v[208:209], v[130:131] op_sel_hi:[1,0]
	v_pk_mul_f32 v[208:209], v[32:33], v[208:209]
	v_pk_mul_f32 v[210:211], v[210:211], v[130:131] op_sel_hi:[1,0]
	v_pk_mul_f32 v[210:211], v[34:35], v[210:211]
	v_pk_mul_f32 v[212:213], v[212:213], v[130:131] op_sel_hi:[1,0]
	v_pk_mul_f32 v[212:213], v[36:37], v[212:213]
	v_pk_mul_f32 v[214:215], v[214:215], v[130:131] op_sel_hi:[1,0]
	v_pk_mul_f32 v[214:215], v[38:39], v[214:215]
	v_cvt_pk_bf16_f32 v136, v208, v209
	v_cvt_pk_bf16_f32 v137, v210, v211
	v_cvt_pk_bf16_f32 v138, v212, v213
	v_cvt_pk_bf16_f32 v139, v214, v215
	global_store_dwordx4 v135, v[136:139], s[14:15] offset:0
	s_nop 1
	v_pk_mul_f32 v[216:217], v[216:217], v[130:131] op_sel_hi:[1,0]
	v_pk_mul_f32 v[216:217], v[40:41], v[216:217]
	v_pk_mul_f32 v[218:219], v[218:219], v[130:131] op_sel_hi:[1,0]
	v_pk_mul_f32 v[218:219], v[42:43], v[218:219]
	v_pk_mul_f32 v[220:221], v[220:221], v[130:131] op_sel_hi:[1,0]
	v_pk_mul_f32 v[220:221], v[44:45], v[220:221]
	v_pk_mul_f32 v[222:223], v[222:223], v[130:131] op_sel_hi:[1,0]
	v_pk_mul_f32 v[222:223], v[46:47], v[222:223]
	v_cvt_pk_bf16_f32 v136, v216, v217
	v_cvt_pk_bf16_f32 v137, v218, v219
	v_cvt_pk_bf16_f32 v138, v220, v221
	v_cvt_pk_bf16_f32 v139, v222, v223
	global_store_dwordx4 v135, v[136:139], s[14:15] offset:1024
	s_nop 1
	v_pk_mul_f32 v[224:225], v[224:225], v[130:131] op_sel_hi:[1,0]
	v_pk_mul_f32 v[224:225], v[48:49], v[224:225]
	v_pk_mul_f32 v[226:227], v[226:227], v[130:131] op_sel_hi:[1,0]
	v_pk_mul_f32 v[226:227], v[50:51], v[226:227]
	v_pk_mul_f32 v[228:229], v[228:229], v[130:131] op_sel_hi:[1,0]
	v_pk_mul_f32 v[228:229], v[52:53], v[228:229]
	v_pk_mul_f32 v[230:231], v[230:231], v[130:131] op_sel_hi:[1,0]
	v_pk_mul_f32 v[230:231], v[54:55], v[230:231]
	v_cvt_pk_bf16_f32 v136, v224, v225
	v_cvt_pk_bf16_f32 v137, v226, v227
	v_cvt_pk_bf16_f32 v138, v228, v229
	v_cvt_pk_bf16_f32 v139, v230, v231
	global_store_dwordx4 v135, v[136:139], s[14:15] offset:2048
	s_nop 1
	v_pk_mul_f32 v[232:233], v[232:233], v[130:131] op_sel_hi:[1,0]
	v_pk_mul_f32 v[232:233], v[56:57], v[232:233]
	v_pk_mul_f32 v[234:235], v[234:235], v[130:131] op_sel_hi:[1,0]
	v_pk_mul_f32 v[234:235], v[58:59], v[234:235]
	v_pk_mul_f32 v[236:237], v[236:237], v[130:131] op_sel_hi:[1,0]
	v_pk_mul_f32 v[236:237], v[60:61], v[236:237]
	v_pk_mul_f32 v[238:239], v[238:239], v[130:131] op_sel_hi:[1,0]
	v_pk_mul_f32 v[238:239], v[62:63], v[238:239]
	v_cvt_pk_bf16_f32 v136, v232, v233
	v_cvt_pk_bf16_f32 v137, v234, v235
	v_cvt_pk_bf16_f32 v138, v236, v237
	v_cvt_pk_bf16_f32 v139, v238, v239
	global_store_dwordx4 v135, v[136:139], s[14:15] offset:3072
	s_nop 1
	s_add_u32 s12, s12, 0x800000
	s_addc_u32 s13, s13, 0
	s_add_u32 s14, s14, 0x800000
	s_addc_u32 s15, s15, 0
	s_waitcnt vmcnt(24)
	v_lshlrev_b32_e32 v208, 16, v160
	v_and_b32_e32 v209, 0xffff0000, v160
	v_lshlrev_b32_e32 v210, 16, v161
	v_and_b32_e32 v211, 0xffff0000, v161
	v_lshlrev_b32_e32 v212, 16, v162
	v_and_b32_e32 v213, 0xffff0000, v162
	v_lshlrev_b32_e32 v214, 16, v163
	v_and_b32_e32 v215, 0xffff0000, v163
	v_lshlrev_b32_e32 v216, 16, v164
	v_and_b32_e32 v217, 0xffff0000, v164
	v_lshlrev_b32_e32 v218, 16, v165
	v_and_b32_e32 v219, 0xffff0000, v165
	v_lshlrev_b32_e32 v220, 16, v166
	v_and_b32_e32 v221, 0xffff0000, v166
	v_lshlrev_b32_e32 v222, 16, v167
	v_and_b32_e32 v223, 0xffff0000, v167
	v_lshlrev_b32_e32 v224, 16, v168
	v_and_b32_e32 v225, 0xffff0000, v168
	v_lshlrev_b32_e32 v226, 16, v169
	v_and_b32_e32 v227, 0xffff0000, v169
	v_lshlrev_b32_e32 v228, 16, v170
	v_and_b32_e32 v229, 0xffff0000, v170
	v_lshlrev_b32_e32 v230, 16, v171
	v_and_b32_e32 v231, 0xffff0000, v171
	v_lshlrev_b32_e32 v232, 16, v172
	v_and_b32_e32 v233, 0xffff0000, v172
	v_lshlrev_b32_e32 v234, 16, v173
	v_and_b32_e32 v235, 0xffff0000, v173
	v_lshlrev_b32_e32 v236, 16, v174
	v_and_b32_e32 v237, 0xffff0000, v174
	v_lshlrev_b32_e32 v238, 16, v175
	v_and_b32_e32 v239, 0xffff0000, v175
	v_mul_f32_e32 v128, v208, v208
	v_fmac_f32_e32 v128, v209, v209
	v_mul_f32_e32 v129, v210, v210
	v_fmac_f32_e32 v129, v211, v211
	v_add_f32_e32 v128, v128, v129
	v_mul_f32_e32 v129, v212, v212
	v_fmac_f32_e32 v129, v213, v213
	v_mul_f32_e32 v132, v214, v214
	v_fmac_f32_e32 v132, v215, v215
	v_add_f32_e32 v129, v129, v132
	v_add_f32_e32 v128, v128, v129
	v_mul_f32_e32 v129, v216, v216
	v_fmac_f32_e32 v129, v217, v217
	v_mul_f32_e32 v132, v218, v218
	v_fmac_f32_e32 v132, v219, v219
	v_add_f32_e32 v129, v129, v132
	v_add_f32_e32 v128, v128, v129
	v_mul_f32_e32 v129, v220, v220
	v_fmac_f32_e32 v129, v221, v221
	v_mul_f32_e32 v132, v222, v222
	v_fmac_f32_e32 v132, v223, v223
	v_add_f32_e32 v129, v129, v132
	v_add_f32_e32 v128, v128, v129
	v_mul_f32_e32 v129, v224, v224
	v_fmac_f32_e32 v129, v225, v225
	v_mul_f32_e32 v132, v226, v226
	v_fmac_f32_e32 v132, v227, v227
	v_add_f32_e32 v129, v129, v132
	v_add_f32_e32 v128, v128, v129
	v_mul_f32_e32 v129, v228, v228
	v_fmac_f32_e32 v129, v229, v229
	v_mul_f32_e32 v132, v230, v230
	v_fmac_f32_e32 v132, v231, v231
	v_add_f32_e32 v129, v129, v132
	v_add_f32_e32 v128, v128, v129
	v_mul_f32_e32 v129, v232, v232
	v_fmac_f32_e32 v129, v233, v233
	v_mul_f32_e32 v132, v234, v234
	v_fmac_f32_e32 v132, v235, v235
	v_add_f32_e32 v129, v129, v132
	v_add_f32_e32 v128, v128, v129
	v_mul_f32_e32 v129, v236, v236
	v_fmac_f32_e32 v129, v237, v237
	v_mul_f32_e32 v132, v238, v238
	v_fmac_f32_e32 v132, v239, v239
	v_add_f32_e32 v129, v129, v132
	v_add_f32_e32 v128, v128, v129
	ds_bpermute_b32 v129, v252, v128
	s_waitcnt lgkmcnt(0)
	v_add_f32_e32 v128, v128, v129
	ds_bpermute_b32 v129, v253, v128
	s_waitcnt lgkmcnt(0)
	v_add_f32_e32 v128, v128, v129
	ds_bpermute_b32 v129, v254, v128
	s_waitcnt lgkmcnt(0)
	v_add_f32_e32 v128, v128, v129
	ds_bpermute_b32 v129, v255, v128
	s_waitcnt lgkmcnt(0)
	v_add_f32_e32 v128, v128, v129
	ds_bpermute_b32 v129, v140, v128
	s_waitcnt lgkmcnt(0)
	v_add_f32_e32 v128, v128, v129
	ds_bpermute_b32 v129, v141, v128
	s_waitcnt lgkmcnt(0)
	v_add_f32_e32 v128, v128, v129
	v_fmamk_f32 v128, v128, 0x3a000000, v133
	v_mul_f32_e32 v129, 0x4b800000, v128
	v_cmp_gt_f32_e32 vcc, s3, v128
	s_nop 1
	v_cndmask_b32_e32 v128, v128, v129, vcc
	v_rsq_f32_e32 v128, v128
	s_nop 0
	v_mul_f32_e32 v129, 0x45800000, v128
	v_cndmask_b32_e32 v130, v128, v129, vcc
	v_lshlrev_b32_e32 v244, 16, v144
	v_and_b32_e32 v245, 0xffff0000, v144
	v_lshlrev_b32_e32 v246, 16, v145
	v_and_b32_e32 v247, 0xffff0000, v145
	v_lshlrev_b32_e32 v248, 16, v146
	v_and_b32_e32 v249, 0xffff0000, v146
	v_lshlrev_b32_e32 v250, 16, v147
	v_and_b32_e32 v251, 0xffff0000, v147
	v_pk_mul_f32 v[208:209], v[130:131], v[208:209] op_sel_hi:[0,1]
	v_pk_fma_f32 v[208:209], v[0:1], v[208:209], v[244:245]
	v_pk_mul_f32 v[210:211], v[130:131], v[210:211] op_sel_hi:[0,1]
	v_pk_fma_f32 v[210:211], v[2:3], v[210:211], v[246:247]
	v_pk_mul_f32 v[212:213], v[130:131], v[212:213] op_sel_hi:[0,1]
	v_pk_fma_f32 v[212:213], v[4:5], v[212:213], v[248:249]
	v_pk_mul_f32 v[214:215], v[130:131], v[214:215] op_sel_hi:[0,1]
	v_pk_fma_f32 v[214:215], v[6:7], v[214:215], v[250:251]
	v_cvt_pk_bf16_f32 v136, v208, v209
	v_cvt_pk_bf16_f32 v137, v210, v211
	v_cvt_pk_bf16_f32 v138, v212, v213
	v_cvt_pk_bf16_f32 v139, v214, v215
	global_store_dwordx4 v135, v[136:139], s[12:13] offset:0
	s_nop 1
	v_lshlrev_b32_e32 v244, 16, v148
	v_and_b32_e32 v245, 0xffff0000, v148
	v_lshlrev_b32_e32 v246, 16, v149
	v_and_b32_e32 v247, 0xffff0000, v149
	v_lshlrev_b32_e32 v248, 16, v150
	v_and_b32_e32 v249, 0xffff0000, v150
	v_lshlrev_b32_e32 v250, 16, v151
	v_and_b32_e32 v251, 0xffff0000, v151
	v_pk_mul_f32 v[216:217], v[130:131], v[216:217] op_sel_hi:[0,1]
	v_pk_fma_f32 v[216:217], v[8:9], v[216:217], v[244:245]
	v_pk_mul_f32 v[218:219], v[130:131], v[218:219] op_sel_hi:[0,1]
	v_pk_fma_f32 v[218:219], v[10:11], v[218:219], v[246:247]
	v_pk_mul_f32 v[220:221], v[130:131], v[220:221] op_sel_hi:[0,1]
	v_pk_fma_f32 v[220:221], v[12:13], v[220:221], v[248:249]
	v_pk_mul_f32 v[222:223], v[130:131], v[222:223] op_sel_hi:[0,1]
	v_pk_fma_f32 v[222:223], v[14:15], v[222:223], v[250:251]
	v_cvt_pk_bf16_f32 v136, v216, v217
	v_cvt_pk_bf16_f32 v137, v218, v219
	v_cvt_pk_bf16_f32 v138, v220, v221
	v_cvt_pk_bf16_f32 v139, v222, v223
	global_store_dwordx4 v135, v[136:139], s[12:13] offset:1024
	s_nop 1
	v_lshlrev_b32_e32 v244, 16, v152
	v_and_b32_e32 v245, 0xffff0000, v152
	v_lshlrev_b32_e32 v246, 16, v153
	v_and_b32_e32 v247, 0xffff0000, v153
	v_lshlrev_b32_e32 v248, 16, v154
	v_and_b32_e32 v249, 0xffff0000, v154
	v_lshlrev_b32_e32 v250, 16, v155
	v_and_b32_e32 v251, 0xffff0000, v155
	v_pk_mul_f32 v[224:225], v[130:131], v[224:225] op_sel_hi:[0,1]
	v_pk_fma_f32 v[224:225], v[16:17], v[224:225], v[244:245]
	v_pk_mul_f32 v[226:227], v[130:131], v[226:227] op_sel_hi:[0,1]
	v_pk_fma_f32 v[226:227], v[18:19], v[226:227], v[246:247]
	v_pk_mul_f32 v[228:229], v[130:131], v[228:229] op_sel_hi:[0,1]
	v_pk_fma_f32 v[228:229], v[20:21], v[228:229], v[248:249]
	v_pk_mul_f32 v[230:231], v[130:131], v[230:231] op_sel_hi:[0,1]
	v_pk_fma_f32 v[230:231], v[22:23], v[230:231], v[250:251]
	v_cvt_pk_bf16_f32 v136, v224, v225
	v_cvt_pk_bf16_f32 v137, v226, v227
	v_cvt_pk_bf16_f32 v138, v228, v229
	v_cvt_pk_bf16_f32 v139, v230, v231
	global_store_dwordx4 v135, v[136:139], s[12:13] offset:2048
	s_nop 1
	v_lshlrev_b32_e32 v244, 16, v156
	v_and_b32_e32 v245, 0xffff0000, v156
	v_lshlrev_b32_e32 v246, 16, v157
	v_and_b32_e32 v247, 0xffff0000, v157
	v_lshlrev_b32_e32 v248, 16, v158
	v_and_b32_e32 v249, 0xffff0000, v158
	v_lshlrev_b32_e32 v250, 16, v159
	v_and_b32_e32 v251, 0xffff0000, v159
	v_pk_mul_f32 v[232:233], v[130:131], v[232:233] op_sel_hi:[0,1]
	v_pk_fma_f32 v[232:233], v[24:25], v[232:233], v[244:245]
	v_pk_mul_f32 v[234:235], v[130:131], v[234:235] op_sel_hi:[0,1]
	v_pk_fma_f32 v[234:235], v[26:27], v[234:235], v[246:247]
	v_pk_mul_f32 v[236:237], v[130:131], v[236:237] op_sel_hi:[0,1]
	v_pk_fma_f32 v[236:237], v[28:29], v[236:237], v[248:249]
	v_pk_mul_f32 v[238:239], v[130:131], v[238:239] op_sel_hi:[0,1]
	v_pk_fma_f32 v[238:239], v[30:31], v[238:239], v[250:251]
	v_cvt_pk_bf16_f32 v136, v232, v233
	v_cvt_pk_bf16_f32 v137, v234, v235
	v_cvt_pk_bf16_f32 v138, v236, v237
	v_cvt_pk_bf16_f32 v139, v238, v239
	global_store_dwordx4 v135, v[136:139], s[12:13] offset:3072
	s_nop 1
	v_mul_f32_e32 v128, v208, v208
	v_fmac_f32_e32 v128, v209, v209
	v_mul_f32_e32 v129, v210, v210
	v_fmac_f32_e32 v129, v211, v211
	v_add_f32_e32 v128, v128, v129
	v_mul_f32_e32 v129, v212, v212
	v_fmac_f32_e32 v129, v213, v213
	v_mul_f32_e32 v132, v214, v214
	v_fmac_f32_e32 v132, v215, v215
	v_add_f32_e32 v129, v129, v132
	v_add_f32_e32 v128, v128, v129
	v_mul_f32_e32 v129, v216, v216
	v_fmac_f32_e32 v129, v217, v217
	v_mul_f32_e32 v132, v218, v218
	v_fmac_f32_e32 v132, v219, v219
	v_add_f32_e32 v129, v129, v132
	v_add_f32_e32 v128, v128, v129
	v_mul_f32_e32 v129, v220, v220
	v_fmac_f32_e32 v129, v221, v221
	v_mul_f32_e32 v132, v222, v222
	v_fmac_f32_e32 v132, v223, v223
	v_add_f32_e32 v129, v129, v132
	v_add_f32_e32 v128, v128, v129
	v_mul_f32_e32 v129, v224, v224
	v_fmac_f32_e32 v129, v225, v225
	v_mul_f32_e32 v132, v226, v226
	v_fmac_f32_e32 v132, v227, v227
	v_add_f32_e32 v129, v129, v132
	v_add_f32_e32 v128, v128, v129
	v_mul_f32_e32 v129, v228, v228
	v_fmac_f32_e32 v129, v229, v229
	v_mul_f32_e32 v132, v230, v230
	v_fmac_f32_e32 v132, v231, v231
	v_add_f32_e32 v129, v129, v132
	v_add_f32_e32 v128, v128, v129
	v_mul_f32_e32 v129, v232, v232
	v_fmac_f32_e32 v129, v233, v233
	v_mul_f32_e32 v132, v234, v234
	v_fmac_f32_e32 v132, v235, v235
	v_add_f32_e32 v129, v129, v132
	v_add_f32_e32 v128, v128, v129
	v_mul_f32_e32 v129, v236, v236
	v_fmac_f32_e32 v129, v237, v237
	v_mul_f32_e32 v132, v238, v238
	v_fmac_f32_e32 v132, v239, v239
	v_add_f32_e32 v129, v129, v132
	v_add_f32_e32 v128, v128, v129
	ds_bpermute_b32 v129, v252, v128
	s_waitcnt lgkmcnt(0)
	v_add_f32_e32 v128, v128, v129
	ds_bpermute_b32 v129, v253, v128
	s_waitcnt lgkmcnt(0)
	v_add_f32_e32 v128, v128, v129
	ds_bpermute_b32 v129, v254, v128
	s_waitcnt lgkmcnt(0)
	v_add_f32_e32 v128, v128, v129
	ds_bpermute_b32 v129, v255, v128
	s_waitcnt lgkmcnt(0)
	v_add_f32_e32 v128, v128, v129
	ds_bpermute_b32 v129, v140, v128
	s_waitcnt lgkmcnt(0)
	v_add_f32_e32 v128, v128, v129
	ds_bpermute_b32 v129, v141, v128
	s_waitcnt lgkmcnt(0)
	v_add_f32_e32 v128, v128, v129
	v_fmamk_f32 v128, v128, 0x3a000000, v133
	v_mul_f32_e32 v129, 0x4b800000, v128
	v_cmp_gt_f32_e32 vcc, s3, v128
	s_nop 1
	v_cndmask_b32_e32 v128, v128, v129, vcc
	v_rsq_f32_e32 v128, v128
	s_nop 0
	v_mul_f32_e32 v129, 0x45800000, v128
	v_cndmask_b32_e32 v130, v128, v129, vcc
	v_pk_mul_f32 v[208:209], v[208:209], v[130:131] op_sel_hi:[1,0]
	v_pk_mul_f32 v[208:209], v[32:33], v[208:209]
	v_pk_mul_f32 v[210:211], v[210:211], v[130:131] op_sel_hi:[1,0]
	v_pk_mul_f32 v[210:211], v[34:35], v[210:211]
	v_pk_mul_f32 v[212:213], v[212:213], v[130:131] op_sel_hi:[1,0]
	v_pk_mul_f32 v[212:213], v[36:37], v[212:213]
	v_pk_mul_f32 v[214:215], v[214:215], v[130:131] op_sel_hi:[1,0]
	v_pk_mul_f32 v[214:215], v[38:39], v[214:215]
	v_cvt_pk_bf16_f32 v136, v208, v209
	v_cvt_pk_bf16_f32 v137, v210, v211
	v_cvt_pk_bf16_f32 v138, v212, v213
	v_cvt_pk_bf16_f32 v139, v214, v215
	global_store_dwordx4 v135, v[136:139], s[14:15] offset:0
	s_nop 1
	v_pk_mul_f32 v[216:217], v[216:217], v[130:131] op_sel_hi:[1,0]
	v_pk_mul_f32 v[216:217], v[40:41], v[216:217]
	v_pk_mul_f32 v[218:219], v[218:219], v[130:131] op_sel_hi:[1,0]
	v_pk_mul_f32 v[218:219], v[42:43], v[218:219]
	v_pk_mul_f32 v[220:221], v[220:221], v[130:131] op_sel_hi:[1,0]
	v_pk_mul_f32 v[220:221], v[44:45], v[220:221]
	v_pk_mul_f32 v[222:223], v[222:223], v[130:131] op_sel_hi:[1,0]
	v_pk_mul_f32 v[222:223], v[46:47], v[222:223]
	v_cvt_pk_bf16_f32 v136, v216, v217
	v_cvt_pk_bf16_f32 v137, v218, v219
	v_cvt_pk_bf16_f32 v138, v220, v221
	v_cvt_pk_bf16_f32 v139, v222, v223
	global_store_dwordx4 v135, v[136:139], s[14:15] offset:1024
	s_nop 1
	v_pk_mul_f32 v[224:225], v[224:225], v[130:131] op_sel_hi:[1,0]
	v_pk_mul_f32 v[224:225], v[48:49], v[224:225]
	v_pk_mul_f32 v[226:227], v[226:227], v[130:131] op_sel_hi:[1,0]
	v_pk_mul_f32 v[226:227], v[50:51], v[226:227]
	v_pk_mul_f32 v[228:229], v[228:229], v[130:131] op_sel_hi:[1,0]
	v_pk_mul_f32 v[228:229], v[52:53], v[228:229]
	v_pk_mul_f32 v[230:231], v[230:231], v[130:131] op_sel_hi:[1,0]
	v_pk_mul_f32 v[230:231], v[54:55], v[230:231]
	v_cvt_pk_bf16_f32 v136, v224, v225
	v_cvt_pk_bf16_f32 v137, v226, v227
	v_cvt_pk_bf16_f32 v138, v228, v229
	v_cvt_pk_bf16_f32 v139, v230, v231
	global_store_dwordx4 v135, v[136:139], s[14:15] offset:2048
	s_nop 1
	v_pk_mul_f32 v[232:233], v[232:233], v[130:131] op_sel_hi:[1,0]
	v_pk_mul_f32 v[232:233], v[56:57], v[232:233]
	v_pk_mul_f32 v[234:235], v[234:235], v[130:131] op_sel_hi:[1,0]
	v_pk_mul_f32 v[234:235], v[58:59], v[234:235]
	v_pk_mul_f32 v[236:237], v[236:237], v[130:131] op_sel_hi:[1,0]
	v_pk_mul_f32 v[236:237], v[60:61], v[236:237]
	v_pk_mul_f32 v[238:239], v[238:239], v[130:131] op_sel_hi:[1,0]
	v_pk_mul_f32 v[238:239], v[62:63], v[238:239]
	v_cvt_pk_bf16_f32 v136, v232, v233
	v_cvt_pk_bf16_f32 v137, v234, v235
	v_cvt_pk_bf16_f32 v138, v236, v237
	v_cvt_pk_bf16_f32 v139, v238, v239
	global_store_dwordx4 v135, v[136:139], s[14:15] offset:3072
	s_nop 1
	s_add_u32 s12, s12, 0x800000
	s_addc_u32 s13, s13, 0
	s_add_u32 s14, s14, 0x800000
	s_addc_u32 s15, s15, 0
	s_waitcnt vmcnt(24)
	v_lshlrev_b32_e32 v208, 16, v192
	v_and_b32_e32 v209, 0xffff0000, v192
	v_lshlrev_b32_e32 v210, 16, v193
	v_and_b32_e32 v211, 0xffff0000, v193
	v_lshlrev_b32_e32 v212, 16, v194
	v_and_b32_e32 v213, 0xffff0000, v194
	v_lshlrev_b32_e32 v214, 16, v195
	v_and_b32_e32 v215, 0xffff0000, v195
	v_lshlrev_b32_e32 v216, 16, v196
	v_and_b32_e32 v217, 0xffff0000, v196
	v_lshlrev_b32_e32 v218, 16, v197
	v_and_b32_e32 v219, 0xffff0000, v197
	v_lshlrev_b32_e32 v220, 16, v198
	v_and_b32_e32 v221, 0xffff0000, v198
	v_lshlrev_b32_e32 v222, 16, v199
	v_and_b32_e32 v223, 0xffff0000, v199
	v_lshlrev_b32_e32 v224, 16, v200
	v_and_b32_e32 v225, 0xffff0000, v200
	v_lshlrev_b32_e32 v226, 16, v201
	v_and_b32_e32 v227, 0xffff0000, v201
	v_lshlrev_b32_e32 v228, 16, v202
	v_and_b32_e32 v229, 0xffff0000, v202
	v_lshlrev_b32_e32 v230, 16, v203
	v_and_b32_e32 v231, 0xffff0000, v203
	v_lshlrev_b32_e32 v232, 16, v204
	v_and_b32_e32 v233, 0xffff0000, v204
	v_lshlrev_b32_e32 v234, 16, v205
	v_and_b32_e32 v235, 0xffff0000, v205
	v_lshlrev_b32_e32 v236, 16, v206
	v_and_b32_e32 v237, 0xffff0000, v206
	v_lshlrev_b32_e32 v238, 16, v207
	v_and_b32_e32 v239, 0xffff0000, v207
	v_mul_f32_e32 v128, v208, v208
	v_fmac_f32_e32 v128, v209, v209
	v_mul_f32_e32 v129, v210, v210
	v_fmac_f32_e32 v129, v211, v211
	v_add_f32_e32 v128, v128, v129
	v_mul_f32_e32 v129, v212, v212
	v_fmac_f32_e32 v129, v213, v213
	v_mul_f32_e32 v132, v214, v214
	v_fmac_f32_e32 v132, v215, v215
	v_add_f32_e32 v129, v129, v132
	v_add_f32_e32 v128, v128, v129
	v_mul_f32_e32 v129, v216, v216
	v_fmac_f32_e32 v129, v217, v217
	v_mul_f32_e32 v132, v218, v218
	v_fmac_f32_e32 v132, v219, v219
	v_add_f32_e32 v129, v129, v132
	v_add_f32_e32 v128, v128, v129
	v_mul_f32_e32 v129, v220, v220
	v_fmac_f32_e32 v129, v221, v221
	v_mul_f32_e32 v132, v222, v222
	v_fmac_f32_e32 v132, v223, v223
	v_add_f32_e32 v129, v129, v132
	v_add_f32_e32 v128, v128, v129
	v_mul_f32_e32 v129, v224, v224
	v_fmac_f32_e32 v129, v225, v225
	v_mul_f32_e32 v132, v226, v226
	v_fmac_f32_e32 v132, v227, v227
	v_add_f32_e32 v129, v129, v132
	v_add_f32_e32 v128, v128, v129
	v_mul_f32_e32 v129, v228, v228
	v_fmac_f32_e32 v129, v229, v229
	v_mul_f32_e32 v132, v230, v230
	v_fmac_f32_e32 v132, v231, v231
	v_add_f32_e32 v129, v129, v132
	v_add_f32_e32 v128, v128, v129
	v_mul_f32_e32 v129, v232, v232
	v_fmac_f32_e32 v129, v233, v233
	v_mul_f32_e32 v132, v234, v234
	v_fmac_f32_e32 v132, v235, v235
	v_add_f32_e32 v129, v129, v132
	v_add_f32_e32 v128, v128, v129
	v_mul_f32_e32 v129, v236, v236
	v_fmac_f32_e32 v129, v237, v237
	v_mul_f32_e32 v132, v238, v238
	v_fmac_f32_e32 v132, v239, v239
	v_add_f32_e32 v129, v129, v132
	v_add_f32_e32 v128, v128, v129
	ds_bpermute_b32 v129, v252, v128
	s_waitcnt lgkmcnt(0)
	v_add_f32_e32 v128, v128, v129
	ds_bpermute_b32 v129, v253, v128
	s_waitcnt lgkmcnt(0)
	v_add_f32_e32 v128, v128, v129
	ds_bpermute_b32 v129, v254, v128
	s_waitcnt lgkmcnt(0)
	v_add_f32_e32 v128, v128, v129
	ds_bpermute_b32 v129, v255, v128
	s_waitcnt lgkmcnt(0)
	v_add_f32_e32 v128, v128, v129
	ds_bpermute_b32 v129, v140, v128
	s_waitcnt lgkmcnt(0)
	v_add_f32_e32 v128, v128, v129
	ds_bpermute_b32 v129, v141, v128
	s_waitcnt lgkmcnt(0)
	v_add_f32_e32 v128, v128, v129
	v_fmamk_f32 v128, v128, 0x3a000000, v133
	v_mul_f32_e32 v129, 0x4b800000, v128
	v_cmp_gt_f32_e32 vcc, s3, v128
	s_nop 1
	v_cndmask_b32_e32 v128, v128, v129, vcc
	v_rsq_f32_e32 v128, v128
	s_nop 0
	v_mul_f32_e32 v129, 0x45800000, v128
	v_cndmask_b32_e32 v130, v128, v129, vcc
	v_lshlrev_b32_e32 v244, 16, v176
	v_and_b32_e32 v245, 0xffff0000, v176
	v_lshlrev_b32_e32 v246, 16, v177
	v_and_b32_e32 v247, 0xffff0000, v177
	v_lshlrev_b32_e32 v248, 16, v178
	v_and_b32_e32 v249, 0xffff0000, v178
	v_lshlrev_b32_e32 v250, 16, v179
	v_and_b32_e32 v251, 0xffff0000, v179
	v_pk_mul_f32 v[208:209], v[130:131], v[208:209] op_sel_hi:[0,1]
	v_pk_fma_f32 v[208:209], v[0:1], v[208:209], v[244:245]
	v_pk_mul_f32 v[210:211], v[130:131], v[210:211] op_sel_hi:[0,1]
	v_pk_fma_f32 v[210:211], v[2:3], v[210:211], v[246:247]
	v_pk_mul_f32 v[212:213], v[130:131], v[212:213] op_sel_hi:[0,1]
	v_pk_fma_f32 v[212:213], v[4:5], v[212:213], v[248:249]
	v_pk_mul_f32 v[214:215], v[130:131], v[214:215] op_sel_hi:[0,1]
	v_pk_fma_f32 v[214:215], v[6:7], v[214:215], v[250:251]
	v_cvt_pk_bf16_f32 v136, v208, v209
	v_cvt_pk_bf16_f32 v137, v210, v211
	v_cvt_pk_bf16_f32 v138, v212, v213
	v_cvt_pk_bf16_f32 v139, v214, v215
	global_store_dwordx4 v135, v[136:139], s[12:13] offset:0
	s_nop 1
	v_lshlrev_b32_e32 v244, 16, v180
	v_and_b32_e32 v245, 0xffff0000, v180
	v_lshlrev_b32_e32 v246, 16, v181
	v_and_b32_e32 v247, 0xffff0000, v181
	v_lshlrev_b32_e32 v248, 16, v182
	v_and_b32_e32 v249, 0xffff0000, v182
	v_lshlrev_b32_e32 v250, 16, v183
	v_and_b32_e32 v251, 0xffff0000, v183
	v_pk_mul_f32 v[216:217], v[130:131], v[216:217] op_sel_hi:[0,1]
	v_pk_fma_f32 v[216:217], v[8:9], v[216:217], v[244:245]
	v_pk_mul_f32 v[218:219], v[130:131], v[218:219] op_sel_hi:[0,1]
	v_pk_fma_f32 v[218:219], v[10:11], v[218:219], v[246:247]
	v_pk_mul_f32 v[220:221], v[130:131], v[220:221] op_sel_hi:[0,1]
	v_pk_fma_f32 v[220:221], v[12:13], v[220:221], v[248:249]
	v_pk_mul_f32 v[222:223], v[130:131], v[222:223] op_sel_hi:[0,1]
	v_pk_fma_f32 v[222:223], v[14:15], v[222:223], v[250:251]
	v_cvt_pk_bf16_f32 v136, v216, v217
	v_cvt_pk_bf16_f32 v137, v218, v219
	v_cvt_pk_bf16_f32 v138, v220, v221
	v_cvt_pk_bf16_f32 v139, v222, v223
	global_store_dwordx4 v135, v[136:139], s[12:13] offset:1024
	s_nop 1
	v_lshlrev_b32_e32 v244, 16, v184
	v_and_b32_e32 v245, 0xffff0000, v184
	v_lshlrev_b32_e32 v246, 16, v185
	v_and_b32_e32 v247, 0xffff0000, v185
	v_lshlrev_b32_e32 v248, 16, v186
	v_and_b32_e32 v249, 0xffff0000, v186
	v_lshlrev_b32_e32 v250, 16, v187
	v_and_b32_e32 v251, 0xffff0000, v187
	v_pk_mul_f32 v[224:225], v[130:131], v[224:225] op_sel_hi:[0,1]
	v_pk_fma_f32 v[224:225], v[16:17], v[224:225], v[244:245]
	v_pk_mul_f32 v[226:227], v[130:131], v[226:227] op_sel_hi:[0,1]
	v_pk_fma_f32 v[226:227], v[18:19], v[226:227], v[246:247]
	v_pk_mul_f32 v[228:229], v[130:131], v[228:229] op_sel_hi:[0,1]
	v_pk_fma_f32 v[228:229], v[20:21], v[228:229], v[248:249]
	v_pk_mul_f32 v[230:231], v[130:131], v[230:231] op_sel_hi:[0,1]
	v_pk_fma_f32 v[230:231], v[22:23], v[230:231], v[250:251]
	v_cvt_pk_bf16_f32 v136, v224, v225
	v_cvt_pk_bf16_f32 v137, v226, v227
	v_cvt_pk_bf16_f32 v138, v228, v229
	v_cvt_pk_bf16_f32 v139, v230, v231
	global_store_dwordx4 v135, v[136:139], s[12:13] offset:2048
	s_nop 1
	v_lshlrev_b32_e32 v244, 16, v188
	v_and_b32_e32 v245, 0xffff0000, v188
	v_lshlrev_b32_e32 v246, 16, v189
	v_and_b32_e32 v247, 0xffff0000, v189
	v_lshlrev_b32_e32 v248, 16, v190
	v_and_b32_e32 v249, 0xffff0000, v190
	v_lshlrev_b32_e32 v250, 16, v191
	v_and_b32_e32 v251, 0xffff0000, v191
	v_pk_mul_f32 v[232:233], v[130:131], v[232:233] op_sel_hi:[0,1]
	v_pk_fma_f32 v[232:233], v[24:25], v[232:233], v[244:245]
	v_pk_mul_f32 v[234:235], v[130:131], v[234:235] op_sel_hi:[0,1]
	v_pk_fma_f32 v[234:235], v[26:27], v[234:235], v[246:247]
	v_pk_mul_f32 v[236:237], v[130:131], v[236:237] op_sel_hi:[0,1]
	v_pk_fma_f32 v[236:237], v[28:29], v[236:237], v[248:249]
	v_pk_mul_f32 v[238:239], v[130:131], v[238:239] op_sel_hi:[0,1]
	v_pk_fma_f32 v[238:239], v[30:31], v[238:239], v[250:251]
	v_cvt_pk_bf16_f32 v136, v232, v233
	v_cvt_pk_bf16_f32 v137, v234, v235
	v_cvt_pk_bf16_f32 v138, v236, v237
	v_cvt_pk_bf16_f32 v139, v238, v239
	global_store_dwordx4 v135, v[136:139], s[12:13] offset:3072
	s_nop 1
	v_mul_f32_e32 v128, v208, v208
	v_fmac_f32_e32 v128, v209, v209
	v_mul_f32_e32 v129, v210, v210
	v_fmac_f32_e32 v129, v211, v211
	v_add_f32_e32 v128, v128, v129
	v_mul_f32_e32 v129, v212, v212
	v_fmac_f32_e32 v129, v213, v213
	v_mul_f32_e32 v132, v214, v214
	v_fmac_f32_e32 v132, v215, v215
	v_add_f32_e32 v129, v129, v132
	v_add_f32_e32 v128, v128, v129
	v_mul_f32_e32 v129, v216, v216
	v_fmac_f32_e32 v129, v217, v217
	v_mul_f32_e32 v132, v218, v218
	v_fmac_f32_e32 v132, v219, v219
	v_add_f32_e32 v129, v129, v132
	v_add_f32_e32 v128, v128, v129
	v_mul_f32_e32 v129, v220, v220
	v_fmac_f32_e32 v129, v221, v221
	v_mul_f32_e32 v132, v222, v222
	v_fmac_f32_e32 v132, v223, v223
	v_add_f32_e32 v129, v129, v132
	v_add_f32_e32 v128, v128, v129
	v_mul_f32_e32 v129, v224, v224
	v_fmac_f32_e32 v129, v225, v225
	v_mul_f32_e32 v132, v226, v226
	v_fmac_f32_e32 v132, v227, v227
	v_add_f32_e32 v129, v129, v132
	v_add_f32_e32 v128, v128, v129
	v_mul_f32_e32 v129, v228, v228
	v_fmac_f32_e32 v129, v229, v229
	v_mul_f32_e32 v132, v230, v230
	v_fmac_f32_e32 v132, v231, v231
	v_add_f32_e32 v129, v129, v132
	v_add_f32_e32 v128, v128, v129
	v_mul_f32_e32 v129, v232, v232
	v_fmac_f32_e32 v129, v233, v233
	v_mul_f32_e32 v132, v234, v234
	v_fmac_f32_e32 v132, v235, v235
	v_add_f32_e32 v129, v129, v132
	v_add_f32_e32 v128, v128, v129
	v_mul_f32_e32 v129, v236, v236
	v_fmac_f32_e32 v129, v237, v237
	v_mul_f32_e32 v132, v238, v238
	v_fmac_f32_e32 v132, v239, v239
	v_add_f32_e32 v129, v129, v132
	v_add_f32_e32 v128, v128, v129
	ds_bpermute_b32 v129, v252, v128
	s_waitcnt lgkmcnt(0)
	v_add_f32_e32 v128, v128, v129
	ds_bpermute_b32 v129, v253, v128
	s_waitcnt lgkmcnt(0)
	v_add_f32_e32 v128, v128, v129
	ds_bpermute_b32 v129, v254, v128
	s_waitcnt lgkmcnt(0)
	v_add_f32_e32 v128, v128, v129
	ds_bpermute_b32 v129, v255, v128
	s_waitcnt lgkmcnt(0)
	v_add_f32_e32 v128, v128, v129
	ds_bpermute_b32 v129, v140, v128
	s_waitcnt lgkmcnt(0)
	v_add_f32_e32 v128, v128, v129
	ds_bpermute_b32 v129, v141, v128
	s_waitcnt lgkmcnt(0)
	v_add_f32_e32 v128, v128, v129
	v_fmamk_f32 v128, v128, 0x3a000000, v133
	v_mul_f32_e32 v129, 0x4b800000, v128
	v_cmp_gt_f32_e32 vcc, s3, v128
	s_nop 1
	v_cndmask_b32_e32 v128, v128, v129, vcc
	v_rsq_f32_e32 v128, v128
	s_nop 0
	v_mul_f32_e32 v129, 0x45800000, v128
	v_cndmask_b32_e32 v130, v128, v129, vcc
	v_pk_mul_f32 v[208:209], v[208:209], v[130:131] op_sel_hi:[1,0]
	v_pk_mul_f32 v[208:209], v[32:33], v[208:209]
	v_pk_mul_f32 v[210:211], v[210:211], v[130:131] op_sel_hi:[1,0]
	v_pk_mul_f32 v[210:211], v[34:35], v[210:211]
	v_pk_mul_f32 v[212:213], v[212:213], v[130:131] op_sel_hi:[1,0]
	v_pk_mul_f32 v[212:213], v[36:37], v[212:213]
	v_pk_mul_f32 v[214:215], v[214:215], v[130:131] op_sel_hi:[1,0]
	v_pk_mul_f32 v[214:215], v[38:39], v[214:215]
	v_cvt_pk_bf16_f32 v136, v208, v209
	v_cvt_pk_bf16_f32 v137, v210, v211
	v_cvt_pk_bf16_f32 v138, v212, v213
	v_cvt_pk_bf16_f32 v139, v214, v215
	global_store_dwordx4 v135, v[136:139], s[14:15] offset:0
	s_nop 1
	v_pk_mul_f32 v[216:217], v[216:217], v[130:131] op_sel_hi:[1,0]
	v_pk_mul_f32 v[216:217], v[40:41], v[216:217]
	v_pk_mul_f32 v[218:219], v[218:219], v[130:131] op_sel_hi:[1,0]
	v_pk_mul_f32 v[218:219], v[42:43], v[218:219]
	v_pk_mul_f32 v[220:221], v[220:221], v[130:131] op_sel_hi:[1,0]
	v_pk_mul_f32 v[220:221], v[44:45], v[220:221]
	v_pk_mul_f32 v[222:223], v[222:223], v[130:131] op_sel_hi:[1,0]
	v_pk_mul_f32 v[222:223], v[46:47], v[222:223]
	v_cvt_pk_bf16_f32 v136, v216, v217
	v_cvt_pk_bf16_f32 v137, v218, v219
	v_cvt_pk_bf16_f32 v138, v220, v221
	v_cvt_pk_bf16_f32 v139, v222, v223
	global_store_dwordx4 v135, v[136:139], s[14:15] offset:1024
	s_nop 1
	v_pk_mul_f32 v[224:225], v[224:225], v[130:131] op_sel_hi:[1,0]
	v_pk_mul_f32 v[224:225], v[48:49], v[224:225]
	v_pk_mul_f32 v[226:227], v[226:227], v[130:131] op_sel_hi:[1,0]
	v_pk_mul_f32 v[226:227], v[50:51], v[226:227]
	v_pk_mul_f32 v[228:229], v[228:229], v[130:131] op_sel_hi:[1,0]
	v_pk_mul_f32 v[228:229], v[52:53], v[228:229]
	v_pk_mul_f32 v[230:231], v[230:231], v[130:131] op_sel_hi:[1,0]
	v_pk_mul_f32 v[230:231], v[54:55], v[230:231]
	v_cvt_pk_bf16_f32 v136, v224, v225
	v_cvt_pk_bf16_f32 v137, v226, v227
	v_cvt_pk_bf16_f32 v138, v228, v229
	v_cvt_pk_bf16_f32 v139, v230, v231
	global_store_dwordx4 v135, v[136:139], s[14:15] offset:2048
	s_nop 1
	v_pk_mul_f32 v[232:233], v[232:233], v[130:131] op_sel_hi:[1,0]
	v_pk_mul_f32 v[232:233], v[56:57], v[232:233]
	v_pk_mul_f32 v[234:235], v[234:235], v[130:131] op_sel_hi:[1,0]
	v_pk_mul_f32 v[234:235], v[58:59], v[234:235]
	v_pk_mul_f32 v[236:237], v[236:237], v[130:131] op_sel_hi:[1,0]
	v_pk_mul_f32 v[236:237], v[60:61], v[236:237]
	v_pk_mul_f32 v[238:239], v[238:239], v[130:131] op_sel_hi:[1,0]
	v_pk_mul_f32 v[238:239], v[62:63], v[238:239]
	v_cvt_pk_bf16_f32 v136, v232, v233
	v_cvt_pk_bf16_f32 v137, v234, v235
	v_cvt_pk_bf16_f32 v138, v236, v237
	v_cvt_pk_bf16_f32 v139, v238, v239
	global_store_dwordx4 v135, v[136:139], s[14:15] offset:3072
	s_nop 1
	s_add_u32 s12, s12, 0x800000
	s_addc_u32 s13, s13, 0
	s_add_u32 s14, s14, 0x800000
	s_addc_u32 s15, s15, 0
	s_cmpk_gt_i32 s10, 0x1ff
	s_cbranch_scc1 .LBB0_1352
	s_waitcnt vmcnt(24)
	v_lshlrev_b32_e32 v208, 16, v80
	v_and_b32_e32 v209, 0xffff0000, v80
	v_lshlrev_b32_e32 v210, 16, v81
	v_and_b32_e32 v211, 0xffff0000, v81
	v_lshlrev_b32_e32 v212, 16, v82
	v_and_b32_e32 v213, 0xffff0000, v82
	v_lshlrev_b32_e32 v214, 16, v83
	v_and_b32_e32 v215, 0xffff0000, v83
	v_lshlrev_b32_e32 v216, 16, v84
	v_and_b32_e32 v217, 0xffff0000, v84
	v_lshlrev_b32_e32 v218, 16, v85
	v_and_b32_e32 v219, 0xffff0000, v85
	v_lshlrev_b32_e32 v220, 16, v86
	v_and_b32_e32 v221, 0xffff0000, v86
	v_lshlrev_b32_e32 v222, 16, v87
	v_and_b32_e32 v223, 0xffff0000, v87
	v_lshlrev_b32_e32 v224, 16, v88
	v_and_b32_e32 v225, 0xffff0000, v88
	v_lshlrev_b32_e32 v226, 16, v89
	v_and_b32_e32 v227, 0xffff0000, v89
	v_lshlrev_b32_e32 v228, 16, v90
	v_and_b32_e32 v229, 0xffff0000, v90
	v_lshlrev_b32_e32 v230, 16, v91
	v_and_b32_e32 v231, 0xffff0000, v91
	v_lshlrev_b32_e32 v232, 16, v92
	v_and_b32_e32 v233, 0xffff0000, v92
	v_lshlrev_b32_e32 v234, 16, v93
	v_and_b32_e32 v235, 0xffff0000, v93
	v_lshlrev_b32_e32 v236, 16, v94
	v_and_b32_e32 v237, 0xffff0000, v94
	v_lshlrev_b32_e32 v238, 16, v95
	v_and_b32_e32 v239, 0xffff0000, v95
	v_mul_f32_e32 v128, v208, v208
	v_fmac_f32_e32 v128, v209, v209
	v_mul_f32_e32 v129, v210, v210
	v_fmac_f32_e32 v129, v211, v211
	v_add_f32_e32 v128, v128, v129
	v_mul_f32_e32 v129, v212, v212
	v_fmac_f32_e32 v129, v213, v213
	v_mul_f32_e32 v132, v214, v214
	v_fmac_f32_e32 v132, v215, v215
	v_add_f32_e32 v129, v129, v132
	v_add_f32_e32 v128, v128, v129
	v_mul_f32_e32 v129, v216, v216
	v_fmac_f32_e32 v129, v217, v217
	v_mul_f32_e32 v132, v218, v218
	v_fmac_f32_e32 v132, v219, v219
	v_add_f32_e32 v129, v129, v132
	v_add_f32_e32 v128, v128, v129
	v_mul_f32_e32 v129, v220, v220
	v_fmac_f32_e32 v129, v221, v221
	v_mul_f32_e32 v132, v222, v222
	v_fmac_f32_e32 v132, v223, v223
	v_add_f32_e32 v129, v129, v132
	v_add_f32_e32 v128, v128, v129
	v_mul_f32_e32 v129, v224, v224
	v_fmac_f32_e32 v129, v225, v225
	v_mul_f32_e32 v132, v226, v226
	v_fmac_f32_e32 v132, v227, v227
	v_add_f32_e32 v129, v129, v132
	v_add_f32_e32 v128, v128, v129
	v_mul_f32_e32 v129, v228, v228
	v_fmac_f32_e32 v129, v229, v229
	v_mul_f32_e32 v132, v230, v230
	v_fmac_f32_e32 v132, v231, v231
	v_add_f32_e32 v129, v129, v132
	v_add_f32_e32 v128, v128, v129
	v_mul_f32_e32 v129, v232, v232
	v_fmac_f32_e32 v129, v233, v233
	v_mul_f32_e32 v132, v234, v234
	v_fmac_f32_e32 v132, v235, v235
	v_add_f32_e32 v129, v129, v132
	v_add_f32_e32 v128, v128, v129
	v_mul_f32_e32 v129, v236, v236
	v_fmac_f32_e32 v129, v237, v237
	v_mul_f32_e32 v132, v238, v238
	v_fmac_f32_e32 v132, v239, v239
	v_add_f32_e32 v129, v129, v132
	v_add_f32_e32 v128, v128, v129
	ds_bpermute_b32 v129, v252, v128
	s_waitcnt lgkmcnt(0)
	v_add_f32_e32 v128, v128, v129
	ds_bpermute_b32 v129, v253, v128
	s_waitcnt lgkmcnt(0)
	v_add_f32_e32 v128, v128, v129
	ds_bpermute_b32 v129, v254, v128
	s_waitcnt lgkmcnt(0)
	v_add_f32_e32 v128, v128, v129
	ds_bpermute_b32 v129, v255, v128
	s_waitcnt lgkmcnt(0)
	v_add_f32_e32 v128, v128, v129
	ds_bpermute_b32 v129, v140, v128
	s_waitcnt lgkmcnt(0)
	v_add_f32_e32 v128, v128, v129
	ds_bpermute_b32 v129, v141, v128
	s_waitcnt lgkmcnt(0)
	v_add_f32_e32 v128, v128, v129
	v_fmamk_f32 v128, v128, 0x3a000000, v133
	v_mul_f32_e32 v129, 0x4b800000, v128
	v_cmp_gt_f32_e32 vcc, s3, v128
	s_nop 1
	v_cndmask_b32_e32 v128, v128, v129, vcc
	v_rsq_f32_e32 v128, v128
	s_nop 0
	v_mul_f32_e32 v129, 0x45800000, v128
	v_cndmask_b32_e32 v130, v128, v129, vcc
	v_lshlrev_b32_e32 v244, 16, v64
	v_and_b32_e32 v245, 0xffff0000, v64
	v_lshlrev_b32_e32 v246, 16, v65
	v_and_b32_e32 v247, 0xffff0000, v65
	v_lshlrev_b32_e32 v248, 16, v66
	v_and_b32_e32 v249, 0xffff0000, v66
	v_lshlrev_b32_e32 v250, 16, v67
	v_and_b32_e32 v251, 0xffff0000, v67
	v_pk_mul_f32 v[208:209], v[130:131], v[208:209] op_sel_hi:[0,1]
	v_pk_fma_f32 v[208:209], v[0:1], v[208:209], v[244:245]
	v_pk_mul_f32 v[210:211], v[130:131], v[210:211] op_sel_hi:[0,1]
	v_pk_fma_f32 v[210:211], v[2:3], v[210:211], v[246:247]
	v_pk_mul_f32 v[212:213], v[130:131], v[212:213] op_sel_hi:[0,1]
	v_pk_fma_f32 v[212:213], v[4:5], v[212:213], v[248:249]
	v_pk_mul_f32 v[214:215], v[130:131], v[214:215] op_sel_hi:[0,1]
	v_pk_fma_f32 v[214:215], v[6:7], v[214:215], v[250:251]
	v_cvt_pk_bf16_f32 v136, v208, v209
	v_cvt_pk_bf16_f32 v137, v210, v211
	v_cvt_pk_bf16_f32 v138, v212, v213
	v_cvt_pk_bf16_f32 v139, v214, v215
	global_store_dwordx4 v135, v[136:139], s[12:13] offset:0
	s_nop 1
	v_lshlrev_b32_e32 v244, 16, v68
	v_and_b32_e32 v245, 0xffff0000, v68
	v_lshlrev_b32_e32 v246, 16, v69
	v_and_b32_e32 v247, 0xffff0000, v69
	v_lshlrev_b32_e32 v248, 16, v70
	v_and_b32_e32 v249, 0xffff0000, v70
	v_lshlrev_b32_e32 v250, 16, v71
	v_and_b32_e32 v251, 0xffff0000, v71
	v_pk_mul_f32 v[216:217], v[130:131], v[216:217] op_sel_hi:[0,1]
	v_pk_fma_f32 v[216:217], v[8:9], v[216:217], v[244:245]
	v_pk_mul_f32 v[218:219], v[130:131], v[218:219] op_sel_hi:[0,1]
	v_pk_fma_f32 v[218:219], v[10:11], v[218:219], v[246:247]
	v_pk_mul_f32 v[220:221], v[130:131], v[220:221] op_sel_hi:[0,1]
	v_pk_fma_f32 v[220:221], v[12:13], v[220:221], v[248:249]
	v_pk_mul_f32 v[222:223], v[130:131], v[222:223] op_sel_hi:[0,1]
	v_pk_fma_f32 v[222:223], v[14:15], v[222:223], v[250:251]
	v_cvt_pk_bf16_f32 v136, v216, v217
	v_cvt_pk_bf16_f32 v137, v218, v219
	v_cvt_pk_bf16_f32 v138, v220, v221
	v_cvt_pk_bf16_f32 v139, v222, v223
	global_store_dwordx4 v135, v[136:139], s[12:13] offset:1024
	s_nop 1
	v_lshlrev_b32_e32 v244, 16, v72
	v_and_b32_e32 v245, 0xffff0000, v72
	v_lshlrev_b32_e32 v246, 16, v73
	v_and_b32_e32 v247, 0xffff0000, v73
	v_lshlrev_b32_e32 v248, 16, v74
	v_and_b32_e32 v249, 0xffff0000, v74
	v_lshlrev_b32_e32 v250, 16, v75
	v_and_b32_e32 v251, 0xffff0000, v75
	v_pk_mul_f32 v[224:225], v[130:131], v[224:225] op_sel_hi:[0,1]
	v_pk_fma_f32 v[224:225], v[16:17], v[224:225], v[244:245]
	v_pk_mul_f32 v[226:227], v[130:131], v[226:227] op_sel_hi:[0,1]
	v_pk_fma_f32 v[226:227], v[18:19], v[226:227], v[246:247]
	v_pk_mul_f32 v[228:229], v[130:131], v[228:229] op_sel_hi:[0,1]
	v_pk_fma_f32 v[228:229], v[20:21], v[228:229], v[248:249]
	v_pk_mul_f32 v[230:231], v[130:131], v[230:231] op_sel_hi:[0,1]
	v_pk_fma_f32 v[230:231], v[22:23], v[230:231], v[250:251]
	v_cvt_pk_bf16_f32 v136, v224, v225
	v_cvt_pk_bf16_f32 v137, v226, v227
	v_cvt_pk_bf16_f32 v138, v228, v229
	v_cvt_pk_bf16_f32 v139, v230, v231
	global_store_dwordx4 v135, v[136:139], s[12:13] offset:2048
	s_nop 1
	v_lshlrev_b32_e32 v244, 16, v76
	v_and_b32_e32 v245, 0xffff0000, v76
	v_lshlrev_b32_e32 v246, 16, v77
	v_and_b32_e32 v247, 0xffff0000, v77
	v_lshlrev_b32_e32 v248, 16, v78
	v_and_b32_e32 v249, 0xffff0000, v78
	v_lshlrev_b32_e32 v250, 16, v79
	v_and_b32_e32 v251, 0xffff0000, v79
	v_pk_mul_f32 v[232:233], v[130:131], v[232:233] op_sel_hi:[0,1]
	v_pk_fma_f32 v[232:233], v[24:25], v[232:233], v[244:245]
	v_pk_mul_f32 v[234:235], v[130:131], v[234:235] op_sel_hi:[0,1]
	v_pk_fma_f32 v[234:235], v[26:27], v[234:235], v[246:247]
	v_pk_mul_f32 v[236:237], v[130:131], v[236:237] op_sel_hi:[0,1]
	v_pk_fma_f32 v[236:237], v[28:29], v[236:237], v[248:249]
	v_pk_mul_f32 v[238:239], v[130:131], v[238:239] op_sel_hi:[0,1]
	v_pk_fma_f32 v[238:239], v[30:31], v[238:239], v[250:251]
	v_cvt_pk_bf16_f32 v136, v232, v233
	v_cvt_pk_bf16_f32 v137, v234, v235
	v_cvt_pk_bf16_f32 v138, v236, v237
	v_cvt_pk_bf16_f32 v139, v238, v239
	global_store_dwordx4 v135, v[136:139], s[12:13] offset:3072
	s_nop 1
	v_mul_f32_e32 v128, v208, v208
	v_fmac_f32_e32 v128, v209, v209
	v_mul_f32_e32 v129, v210, v210
	v_fmac_f32_e32 v129, v211, v211
	v_add_f32_e32 v128, v128, v129
	v_mul_f32_e32 v129, v212, v212
	v_fmac_f32_e32 v129, v213, v213
	v_mul_f32_e32 v132, v214, v214
	v_fmac_f32_e32 v132, v215, v215
	v_add_f32_e32 v129, v129, v132
	v_add_f32_e32 v128, v128, v129
	v_mul_f32_e32 v129, v216, v216
	v_fmac_f32_e32 v129, v217, v217
	v_mul_f32_e32 v132, v218, v218
	v_fmac_f32_e32 v132, v219, v219
	v_add_f32_e32 v129, v129, v132
	v_add_f32_e32 v128, v128, v129
	v_mul_f32_e32 v129, v220, v220
	v_fmac_f32_e32 v129, v221, v221
	v_mul_f32_e32 v132, v222, v222
	v_fmac_f32_e32 v132, v223, v223
	v_add_f32_e32 v129, v129, v132
	v_add_f32_e32 v128, v128, v129
	v_mul_f32_e32 v129, v224, v224
	v_fmac_f32_e32 v129, v225, v225
	v_mul_f32_e32 v132, v226, v226
	v_fmac_f32_e32 v132, v227, v227
	v_add_f32_e32 v129, v129, v132
	v_add_f32_e32 v128, v128, v129
	v_mul_f32_e32 v129, v228, v228
	v_fmac_f32_e32 v129, v229, v229
	v_mul_f32_e32 v132, v230, v230
	v_fmac_f32_e32 v132, v231, v231
	v_add_f32_e32 v129, v129, v132
	v_add_f32_e32 v128, v128, v129
	v_mul_f32_e32 v129, v232, v232
	v_fmac_f32_e32 v129, v233, v233
	v_mul_f32_e32 v132, v234, v234
	v_fmac_f32_e32 v132, v235, v235
	v_add_f32_e32 v129, v129, v132
	v_add_f32_e32 v128, v128, v129
	v_mul_f32_e32 v129, v236, v236
	v_fmac_f32_e32 v129, v237, v237
	v_mul_f32_e32 v132, v238, v238
	v_fmac_f32_e32 v132, v239, v239
	v_add_f32_e32 v129, v129, v132
	v_add_f32_e32 v128, v128, v129
	ds_bpermute_b32 v129, v252, v128
	s_waitcnt lgkmcnt(0)
	v_add_f32_e32 v128, v128, v129
	ds_bpermute_b32 v129, v253, v128
	s_waitcnt lgkmcnt(0)
	v_add_f32_e32 v128, v128, v129
	ds_bpermute_b32 v129, v254, v128
	s_waitcnt lgkmcnt(0)
	v_add_f32_e32 v128, v128, v129
	ds_bpermute_b32 v129, v255, v128
	s_waitcnt lgkmcnt(0)
	v_add_f32_e32 v128, v128, v129
	ds_bpermute_b32 v129, v140, v128
	s_waitcnt lgkmcnt(0)
	v_add_f32_e32 v128, v128, v129
	ds_bpermute_b32 v129, v141, v128
	s_waitcnt lgkmcnt(0)
	v_add_f32_e32 v128, v128, v129
	v_fmamk_f32 v128, v128, 0x3a000000, v133
	v_mul_f32_e32 v129, 0x4b800000, v128
	v_cmp_gt_f32_e32 vcc, s3, v128
	s_nop 1
	v_cndmask_b32_e32 v128, v128, v129, vcc
	v_rsq_f32_e32 v128, v128
	s_nop 0
	v_mul_f32_e32 v129, 0x45800000, v128
	v_cndmask_b32_e32 v130, v128, v129, vcc
	v_pk_mul_f32 v[208:209], v[208:209], v[130:131] op_sel_hi:[1,0]
	v_pk_mul_f32 v[208:209], v[32:33], v[208:209]
	v_pk_mul_f32 v[210:211], v[210:211], v[130:131] op_sel_hi:[1,0]
	v_pk_mul_f32 v[210:211], v[34:35], v[210:211]
	v_pk_mul_f32 v[212:213], v[212:213], v[130:131] op_sel_hi:[1,0]
	v_pk_mul_f32 v[212:213], v[36:37], v[212:213]
	v_pk_mul_f32 v[214:215], v[214:215], v[130:131] op_sel_hi:[1,0]
	v_pk_mul_f32 v[214:215], v[38:39], v[214:215]
	v_cvt_pk_bf16_f32 v136, v208, v209
	v_cvt_pk_bf16_f32 v137, v210, v211
	v_cvt_pk_bf16_f32 v138, v212, v213
	v_cvt_pk_bf16_f32 v139, v214, v215
	global_store_dwordx4 v135, v[136:139], s[14:15] offset:0
	s_nop 1
	v_pk_mul_f32 v[216:217], v[216:217], v[130:131] op_sel_hi:[1,0]
	v_pk_mul_f32 v[216:217], v[40:41], v[216:217]
	v_pk_mul_f32 v[218:219], v[218:219], v[130:131] op_sel_hi:[1,0]
	v_pk_mul_f32 v[218:219], v[42:43], v[218:219]
	v_pk_mul_f32 v[220:221], v[220:221], v[130:131] op_sel_hi:[1,0]
	v_pk_mul_f32 v[220:221], v[44:45], v[220:221]
	v_pk_mul_f32 v[222:223], v[222:223], v[130:131] op_sel_hi:[1,0]
	v_pk_mul_f32 v[222:223], v[46:47], v[222:223]
	v_cvt_pk_bf16_f32 v136, v216, v217
	v_cvt_pk_bf16_f32 v137, v218, v219
	v_cvt_pk_bf16_f32 v138, v220, v221
	v_cvt_pk_bf16_f32 v139, v222, v223
	global_store_dwordx4 v135, v[136:139], s[14:15] offset:1024
	s_nop 1
	v_pk_mul_f32 v[224:225], v[224:225], v[130:131] op_sel_hi:[1,0]
	v_pk_mul_f32 v[224:225], v[48:49], v[224:225]
	v_pk_mul_f32 v[226:227], v[226:227], v[130:131] op_sel_hi:[1,0]
	v_pk_mul_f32 v[226:227], v[50:51], v[226:227]
	v_pk_mul_f32 v[228:229], v[228:229], v[130:131] op_sel_hi:[1,0]
	v_pk_mul_f32 v[228:229], v[52:53], v[228:229]
	v_pk_mul_f32 v[230:231], v[230:231], v[130:131] op_sel_hi:[1,0]
	v_pk_mul_f32 v[230:231], v[54:55], v[230:231]
	v_cvt_pk_bf16_f32 v136, v224, v225
	v_cvt_pk_bf16_f32 v137, v226, v227
	v_cvt_pk_bf16_f32 v138, v228, v229
	v_cvt_pk_bf16_f32 v139, v230, v231
	global_store_dwordx4 v135, v[136:139], s[14:15] offset:2048
	s_nop 1
	v_pk_mul_f32 v[232:233], v[232:233], v[130:131] op_sel_hi:[1,0]
	v_pk_mul_f32 v[232:233], v[56:57], v[232:233]
	v_pk_mul_f32 v[234:235], v[234:235], v[130:131] op_sel_hi:[1,0]
	v_pk_mul_f32 v[234:235], v[58:59], v[234:235]
	v_pk_mul_f32 v[236:237], v[236:237], v[130:131] op_sel_hi:[1,0]
	v_pk_mul_f32 v[236:237], v[60:61], v[236:237]
	v_pk_mul_f32 v[238:239], v[238:239], v[130:131] op_sel_hi:[1,0]
	v_pk_mul_f32 v[238:239], v[62:63], v[238:239]
	v_cvt_pk_bf16_f32 v136, v232, v233
	v_cvt_pk_bf16_f32 v137, v234, v235
	v_cvt_pk_bf16_f32 v138, v236, v237
	v_cvt_pk_bf16_f32 v139, v238, v239
	global_store_dwordx4 v135, v[136:139], s[14:15] offset:3072
	s_nop 1
	s_add_u32 s12, s12, 0x800000
	s_addc_u32 s13, s13, 0
	s_add_u32 s14, s14, 0x800000
	s_addc_u32 s15, s15, 0
